# static priority: s_setprio 2 around the P9 4x4x4 MFMA runs, 0 after
# baseline (speedup 1.0000x reference)
; #define LAS __attribute__((address_space(3)))
; #define WAVE_LDS_FENCE() asm volatile("s_waitcnt lgkmcnt(0)" ::: "memory")
; __device__ __forceinline__ void s5_out_phase(LAS unsigned char* lds, const bf16_t* UZ, const unsigned char* ws, const float* dskip, bf16_t* YG) {
;     ...
;         for (int mm = 0; mm < 4; ++mm) {
;             const int mf = mm, mb = 3 - mm;
; #pragma unroll
;             for (int nt = 0; nt < 8; ++nt) {
;                 const f32x4 z = {0.f, 0.f, 0.f, 0.f};
;                 const f32x4 cf = __builtin_amdgcn_mfma_f32_16x16x16bf16_1k(Uf[mf], Bf[0][nt], z, 0, 0, 0);
;                 const f32x4 cb = __builtin_amdgcn_mfma_f32_16x16x16bf16_1k(Uf[mb], Bf[1][nt], z, 0, 0, 0);
;                 u32x2 wf, wb; wf.x = pk2(cf[0], cf[1]); wf.y = pk2(cf[2], cf[3]); wb.x = pk2(cb[0], cb[1]); wb.y = pk2(cb[2], cb[3]);
;                 *(LAS u32x2*)(wl + nt * 640 + wofs) = wf;
;                 *(LAS u32x2*)(wl + BUT_BYTES + nt * 640 + wofs) = wb;
;             }
;             WAVE_LDS_FENCE();
;             const LAS unsigned char* rp = wl + lane * 80;
;             const u32x4 fre0 = *(const LAS u32x4*)(rp), fre1 = *(const LAS u32x4*)(rp + 16), fim0 = *(const LAS u32x4*)(rp + 32), fim1 = *(const LAS u32x4*)(rp + 48);
;             const u32x4 bre0 = *(const LAS u32x4*)(rp + BUT_BYTES), bre1 = *(const LAS u32x4*)(rp + BUT_BYTES + 16), bim0 = *(const LAS u32x4*)(rp + BUT_BYTES + 32), bim1 = *(const LAS u32x4*)(rp + BUT_BYTES + 48);
;             LAS unsigned char* xf = wl + 2 * BUT_BYTES; LAS unsigned char* xbk = xf + XB_BYTES;
; #pragma unroll
;             for (int rr = 0; rr < 16; ++rr) {
;                 const int r = rr, rb = 15 - rr;
;                 { const f32x2 bb = {bf_at(fre0, fre1, r), bf_at(fim0, fim1, r)};
;                   const f32x2 n2 = cmac((f32x2){xfr, xfi}, (f32x2){ap[0].x, ap[0].x}, (f32x2){-ap[0].y, ap[0].y}, bb); xfr = n2.x; xfi = n2.y;
;                   *(LAS unsigned*)(xf + r * XB_PITCH + lane * 4) = pk2(n2.x, n2.y); }
;                 { const f32x2 bb = {bf_at(bre0, bre1, rb), bf_at(bim0, bim1, rb)};
;                   const f32x2 n2 = cmac((f32x2){xbr, xbi}, (f32x2){ap[1].x, ap[1].x}, (f32x2){-ap[1].y, ap[1].y}, bb); xbr = n2.x; xbi = n2.y;
;                   *(LAS unsigned*)(xbk + rb * XB_PITCH + lane * 4) = pk2(n2.x, n2.y); }
;             }
.LBB0_755:
	v_mov_b32_e32 v114, v44
	v_mov_b32_e32 v119, v45
	v_mov_b32_e32 v121, v46
	v_mov_b32_e32 v127, v47
	s_setprio 2
	v_mfma_f32_4x4x4_16b_bf16 v[188:191], v[172:173], v[60:61], 0 cbsz:4 abid:0
	v_mfma_f32_4x4x4_16b_bf16 v[194:197], v[172:173], v[68:69], 0 cbsz:4 abid:0
	v_mfma_f32_4x4x4_16b_bf16 v[198:201], v[172:173], v[60:61], 0 cbsz:4 abid:1
	v_mfma_f32_4x4x4_16b_bf16 v[202:205], v[172:173], v[68:69], 0 cbsz:4 abid:1
	v_mfma_f32_4x4x4_16b_bf16 v[206:209], v[172:173], v[60:61], 0 cbsz:4 abid:2
	v_mfma_f32_4x4x4_16b_bf16 v[210:213], v[172:173], v[68:69], 0 cbsz:4 abid:2
	v_mfma_f32_4x4x4_16b_bf16 v[214:217], v[172:173], v[60:61], 0 cbsz:4 abid:3
	v_mfma_f32_4x4x4_16b_bf16 v[218:221], v[172:173], v[68:69], 0 cbsz:4 abid:3
	v_mfma_f32_4x4x4_16b_bf16 v[222:225], v[116:117], v[76:77], 0 cbsz:4 abid:0
	v_mfma_f32_4x4x4_16b_bf16 v[226:229], v[116:117], v[84:85], 0 cbsz:4 abid:0
	v_mfma_f32_4x4x4_16b_bf16 v[230:233], v[116:117], v[76:77], 0 cbsz:4 abid:1
	v_mfma_f32_4x4x4_16b_bf16 v[234:237], v[116:117], v[84:85], 0 cbsz:4 abid:1
	v_mfma_f32_4x4x4_16b_bf16 v[238:241], v[116:117], v[76:77], 0 cbsz:4 abid:2
	v_mfma_f32_4x4x4_16b_bf16 v[242:245], v[116:117], v[84:85], 0 cbsz:4 abid:2
	v_mfma_f32_4x4x4_16b_bf16 v[246:249], v[116:117], v[76:77], 0 cbsz:4 abid:3
	v_mfma_f32_4x4x4_16b_bf16 v[250:253], v[116:117], v[84:85], 0 cbsz:4 abid:3
	v_mfma_f32_4x4x4_16b_bf16 v[188:191], v[172:173], v[62:63], v[188:191] cbsz:4 abid:4
	v_mfma_f32_4x4x4_16b_bf16 v[194:197], v[172:173], v[70:71], v[194:197] cbsz:4 abid:4
	v_mfma_f32_4x4x4_16b_bf16 v[198:201], v[172:173], v[62:63], v[198:201] cbsz:4 abid:5
	v_mfma_f32_4x4x4_16b_bf16 v[202:205], v[172:173], v[70:71], v[202:205] cbsz:4 abid:5
	v_mfma_f32_4x4x4_16b_bf16 v[206:209], v[172:173], v[62:63], v[206:209] cbsz:4 abid:6
	v_mfma_f32_4x4x4_16b_bf16 v[210:213], v[172:173], v[70:71], v[210:213] cbsz:4 abid:6
	v_mfma_f32_4x4x4_16b_bf16 v[214:217], v[172:173], v[62:63], v[214:217] cbsz:4 abid:7
	v_mfma_f32_4x4x4_16b_bf16 v[218:221], v[172:173], v[70:71], v[218:221] cbsz:4 abid:7
	v_mfma_f32_4x4x4_16b_bf16 v[222:225], v[116:117], v[78:79], v[222:225] cbsz:4 abid:4
	v_mfma_f32_4x4x4_16b_bf16 v[226:229], v[116:117], v[86:87], v[226:229] cbsz:4 abid:4
	v_mfma_f32_4x4x4_16b_bf16 v[230:233], v[116:117], v[78:79], v[230:233] cbsz:4 abid:5
	v_mfma_f32_4x4x4_16b_bf16 v[234:237], v[116:117], v[86:87], v[234:237] cbsz:4 abid:5
	v_mfma_f32_4x4x4_16b_bf16 v[238:241], v[116:117], v[78:79], v[238:241] cbsz:4 abid:6
	v_mfma_f32_4x4x4_16b_bf16 v[242:245], v[116:117], v[86:87], v[242:245] cbsz:4 abid:6
	v_mfma_f32_4x4x4_16b_bf16 v[246:249], v[116:117], v[78:79], v[246:249] cbsz:4 abid:7
	v_mfma_f32_4x4x4_16b_bf16 v[250:253], v[116:117], v[86:87], v[250:253] cbsz:4 abid:7
	v_mfma_f32_4x4x4_16b_bf16 v[188:191], v[172:173], v[64:65], v[188:191] cbsz:4 abid:8
	v_mfma_f32_4x4x4_16b_bf16 v[194:197], v[172:173], v[72:73], v[194:197] cbsz:4 abid:8
	v_mfma_f32_4x4x4_16b_bf16 v[198:201], v[172:173], v[64:65], v[198:201] cbsz:4 abid:9
	v_mfma_f32_4x4x4_16b_bf16 v[202:205], v[172:173], v[72:73], v[202:205] cbsz:4 abid:9
	v_mfma_f32_4x4x4_16b_bf16 v[206:209], v[172:173], v[64:65], v[206:209] cbsz:4 abid:10
	v_mfma_f32_4x4x4_16b_bf16 v[210:213], v[172:173], v[72:73], v[210:213] cbsz:4 abid:10
	v_mfma_f32_4x4x4_16b_bf16 v[214:217], v[172:173], v[64:65], v[214:217] cbsz:4 abid:11
	v_mfma_f32_4x4x4_16b_bf16 v[218:221], v[172:173], v[72:73], v[218:221] cbsz:4 abid:11
	v_mfma_f32_4x4x4_16b_bf16 v[222:225], v[116:117], v[80:81], v[222:225] cbsz:4 abid:8
	v_mfma_f32_4x4x4_16b_bf16 v[226:229], v[116:117], v[88:89], v[226:229] cbsz:4 abid:8
	v_mfma_f32_4x4x4_16b_bf16 v[230:233], v[116:117], v[80:81], v[230:233] cbsz:4 abid:9
	v_mfma_f32_4x4x4_16b_bf16 v[234:237], v[116:117], v[88:89], v[234:237] cbsz:4 abid:9
	v_mfma_f32_4x4x4_16b_bf16 v[238:241], v[116:117], v[80:81], v[238:241] cbsz:4 abid:10
	v_mfma_f32_4x4x4_16b_bf16 v[242:245], v[116:117], v[88:89], v[242:245] cbsz:4 abid:10
	v_mfma_f32_4x4x4_16b_bf16 v[246:249], v[116:117], v[80:81], v[246:249] cbsz:4 abid:11
	v_mfma_f32_4x4x4_16b_bf16 v[250:253], v[116:117], v[88:89], v[250:253] cbsz:4 abid:11
	v_mfma_f32_4x4x4_16b_bf16 v[188:191], v[172:173], v[66:67], v[188:191] cbsz:4 abid:12
	v_mfma_f32_4x4x4_16b_bf16 v[194:197], v[172:173], v[74:75], v[194:197] cbsz:4 abid:12
	v_mfma_f32_4x4x4_16b_bf16 v[198:201], v[172:173], v[66:67], v[198:201] cbsz:4 abid:13
	v_mfma_f32_4x4x4_16b_bf16 v[202:205], v[172:173], v[74:75], v[202:205] cbsz:4 abid:13
	v_mfma_f32_4x4x4_16b_bf16 v[206:209], v[172:173], v[66:67], v[206:209] cbsz:4 abid:14
	v_mfma_f32_4x4x4_16b_bf16 v[210:213], v[172:173], v[74:75], v[210:213] cbsz:4 abid:14
	v_mfma_f32_4x4x4_16b_bf16 v[214:217], v[172:173], v[66:67], v[214:217] cbsz:4 abid:15
	v_mfma_f32_4x4x4_16b_bf16 v[218:221], v[172:173], v[74:75], v[218:221] cbsz:4 abid:15
	v_mfma_f32_4x4x4_16b_bf16 v[222:225], v[116:117], v[82:83], v[222:225] cbsz:4 abid:12
	v_mfma_f32_4x4x4_16b_bf16 v[226:229], v[116:117], v[90:91], v[226:229] cbsz:4 abid:12
	v_mfma_f32_4x4x4_16b_bf16 v[230:233], v[116:117], v[82:83], v[230:233] cbsz:4 abid:13
	v_mfma_f32_4x4x4_16b_bf16 v[234:237], v[116:117], v[90:91], v[234:237] cbsz:4 abid:13
	v_mfma_f32_4x4x4_16b_bf16 v[238:241], v[116:117], v[82:83], v[238:241] cbsz:4 abid:14
	v_mfma_f32_4x4x4_16b_bf16 v[242:245], v[116:117], v[90:91], v[242:245] cbsz:4 abid:14
	v_mfma_f32_4x4x4_16b_bf16 v[246:249], v[116:117], v[82:83], v[246:249] cbsz:4 abid:15
	v_mfma_f32_4x4x4_16b_bf16 v[250:253], v[116:117], v[90:91], v[250:253] cbsz:4 abid:15
	s_setprio 0
	v_fma_f32 v188, v150, v114, v188
	v_fma_f32 v194, v150, v119, v194
	v_fma_f32 v188, v16, v119, v188
	v_fma_f32 v194, v17, v114, v194
; #define LAS __attribute__((address_space(3)))
; __device__ __forceinline__ unsigned pk2(float lo, float hi) { f32x2 v = {lo, hi}; nbf2 r = __builtin_convertvector(v, nbf2); return __builtin_bit_cast(unsigned, r); }
; #define WAVE_LDS_FENCE() asm volatile("s_waitcnt lgkmcnt(0)" ::: "memory")
; __device__ __forceinline__ float bf_at(const u32x4& lo, const u32x4& hi, int r) { const unsigned w = (r < 8 ? lo : hi)[(r & 7) >> 1]; return (r & 1) ? bf_hi(w) : bf_lo(w); }
; __device__ __forceinline__ void s5_out_phase(LAS unsigned char* lds, const bf16_t* UZ, const unsigned char* ws, const float* dskip, bf16_t* YG) {
;     ...
; #pragma unroll
;             for (int rr = 0; rr < 16; ++rr) {
;                 const int r = rr, rb = 15 - rr;
;                 { const f32x2 bb = {bf_at(fre0, fre1, r), bf_at(fim0, fim1, r)};
;                   const f32x2 n2 = cmac((f32x2){xfr, xfi}, (f32x2){ap[0].x, ap[0].x}, (f32x2){-ap[0].y, ap[0].y}, bb); xfr = n2.x; xfi = n2.y;
;                   *(LAS unsigned*)(xf + r * XB_PITCH + lane * 4) = pk2(n2.x, n2.y); }
;                 { const f32x2 bb = {bf_at(bre0, bre1, rb), bf_at(bim0, bim1, rb)};
;                   const f32x2 n2 = cmac((f32x2){xbr, xbi}, (f32x2){ap[1].x, ap[1].x}, (f32x2){-ap[1].y, ap[1].y}, bb); xbr = n2.x; xbi = n2.y;
;                   *(LAS unsigned*)(xbk + rb * XB_PITCH + lane * 4) = pk2(n2.x, n2.y); }
;             }
;             WAVE_LDS_FENCE();
; #pragma unroll
;             for (int ks = 0; ks < 4; ++ks) {
;                 const bf16x8 Xf = *(const LAS bf16x8*)(xf + fr * XB_PITCH + (8 * fq + 32 * ks) * 2);
;                 const bf16x8 Xb = *(const LAS bf16x8*)(xbk + fr * XB_PITCH + (8 * fq + 32 * ks) * 2);
	v_fma_f32 v249, v152, v121, v249
	v_fma_f32 v253, v152, v127, v253
	v_fma_f32 v249, v36, v127, v249
	v_fma_f32 v253, v37, v121, v253
	v_cvt_pk_bf16_f32 v128, v188, v194
	v_cvt_pk_bf16_f32 v136, v249, v253
	v_add_u32_e32 v193, 0x2800, v103
	v_add_u32_e32 v254, 0x45c0, v103
	v_fma_f32 v189, v150, v188, v189
	v_fma_f32 v195, v150, v194, v195
	v_fma_f32 v189, v16, v194, v189
	v_fma_f32 v195, v17, v188, v195
	v_fma_f32 v248, v152, v249, v248
	v_fma_f32 v252, v152, v253, v252
	v_fma_f32 v248, v36, v253, v248
	v_fma_f32 v252, v37, v249, v252
	v_cvt_pk_bf16_f32 v131, v189, v195
	v_cvt_pk_bf16_f32 v139, v248, v252
	ds_write2_b32 v193, v128, v131 offset0:0 offset1:68
	ds_write2_b32 v254, v139, v136 offset0:136 offset1:204
	v_fma_f32 v190, v150, v189, v190
	v_fma_f32 v196, v150, v195, v196
	v_fma_f32 v190, v16, v195, v190
	v_fma_f32 v196, v17, v189, v196
	v_fma_f32 v247, v152, v248, v247
	v_fma_f32 v251, v152, v252, v251
	v_fma_f32 v247, v36, v252, v247
	v_fma_f32 v251, v37, v248, v251
	v_cvt_pk_bf16_f32 v132, v190, v196
	v_cvt_pk_bf16_f32 v143, v247, v251
	v_fma_f32 v191, v150, v190, v191
	v_fma_f32 v197, v150, v196, v197
	v_fma_f32 v191, v16, v196, v191
	v_fma_f32 v197, v17, v190, v197
	v_fma_f32 v246, v152, v247, v246
	v_fma_f32 v250, v152, v251, v250
	v_fma_f32 v246, v36, v251, v246
	v_fma_f32 v250, v37, v247, v250
	v_cvt_pk_bf16_f32 v135, v191, v197
	v_cvt_pk_bf16_f32 v187, v246, v250
	ds_write2_b32 v193, v132, v135 offset0:136 offset1:204
	ds_write2_b32 v254, v187, v143 offset0:0 offset1:68
	v_fma_f32 v198, v150, v191, v198
	v_fma_f32 v202, v150, v197, v202
	v_fma_f32 v198, v16, v197, v198
	v_fma_f32 v202, v17, v191, v202
	v_fma_f32 v241, v152, v246, v241
	v_fma_f32 v245, v152, v250, v245
	v_fma_f32 v241, v36, v250, v241
	v_fma_f32 v245, v37, v246, v245
	v_cvt_pk_bf16_f32 v128, v198, v202
	v_cvt_pk_bf16_f32 v136, v241, v245
	v_add_u32_e32 v193, 0x2c40, v103
	v_add_u32_e32 v254, 0x4180, v103
	v_fma_f32 v199, v150, v198, v199
	v_fma_f32 v203, v150, v202, v203
	v_fma_f32 v199, v16, v202, v199
	v_fma_f32 v203, v17, v198, v203
	v_fma_f32 v240, v152, v241, v240
	v_fma_f32 v244, v152, v245, v244
	v_fma_f32 v240, v36, v245, v240
	v_fma_f32 v244, v37, v241, v244
	v_cvt_pk_bf16_f32 v131, v199, v203
	v_cvt_pk_bf16_f32 v139, v240, v244
	ds_write2_b32 v193, v128, v131 offset0:0 offset1:68
	ds_write2_b32 v254, v139, v136 offset0:136 offset1:204
	v_fma_f32 v200, v150, v199, v200
	v_fma_f32 v204, v150, v203, v204
	v_fma_f32 v200, v16, v203, v200
	v_fma_f32 v204, v17, v199, v204
	v_fma_f32 v239, v152, v240, v239
	v_fma_f32 v243, v152, v244, v243
	v_fma_f32 v239, v36, v244, v239
	v_fma_f32 v243, v37, v240, v243
	v_cvt_pk_bf16_f32 v132, v200, v204
	v_cvt_pk_bf16_f32 v143, v239, v243
	v_fma_f32 v201, v150, v200, v201
	v_fma_f32 v205, v150, v204, v205
	v_fma_f32 v201, v16, v204, v201
	v_fma_f32 v205, v17, v200, v205
	v_fma_f32 v238, v152, v239, v238
	v_fma_f32 v242, v152, v243, v242
	v_fma_f32 v238, v36, v243, v238
	v_fma_f32 v242, v37, v239, v242
	v_cvt_pk_bf16_f32 v135, v201, v205
	v_cvt_pk_bf16_f32 v187, v238, v242
	ds_write2_b32 v193, v132, v135 offset0:136 offset1:204
	ds_write2_b32 v254, v187, v143 offset0:0 offset1:68
	v_fma_f32 v206, v150, v201, v206
	v_fma_f32 v210, v150, v205, v210
	v_fma_f32 v206, v16, v205, v206
	v_fma_f32 v210, v17, v201, v210
	v_fma_f32 v233, v152, v238, v233
	v_fma_f32 v237, v152, v242, v237
	v_fma_f32 v233, v36, v242, v233
	v_fma_f32 v237, v37, v238, v237
	v_cvt_pk_bf16_f32 v128, v206, v210
	v_cvt_pk_bf16_f32 v136, v233, v237
	v_add_u32_e32 v193, 0x3080, v103
	v_add_u32_e32 v254, 0x3d40, v103
	v_fma_f32 v207, v150, v206, v207
	v_fma_f32 v211, v150, v210, v211
	v_fma_f32 v207, v16, v210, v207
	v_fma_f32 v211, v17, v206, v211
	v_fma_f32 v232, v152, v233, v232
	v_fma_f32 v236, v152, v237, v236
	v_fma_f32 v232, v36, v237, v232
	v_fma_f32 v236, v37, v233, v236
	v_cvt_pk_bf16_f32 v131, v207, v211
	v_cvt_pk_bf16_f32 v139, v232, v236
	ds_write2_b32 v193, v128, v131 offset0:0 offset1:68
	ds_write2_b32 v254, v139, v136 offset0:136 offset1:204
	v_fma_f32 v208, v150, v207, v208
	v_fma_f32 v212, v150, v211, v212
	v_fma_f32 v208, v16, v211, v208
	v_fma_f32 v212, v17, v207, v212
	v_fma_f32 v231, v152, v232, v231
	v_fma_f32 v235, v152, v236, v235
	v_fma_f32 v231, v36, v236, v231
	v_fma_f32 v235, v37, v232, v235
	v_cvt_pk_bf16_f32 v132, v208, v212
	v_cvt_pk_bf16_f32 v143, v231, v235
	v_fma_f32 v209, v150, v208, v209
	v_fma_f32 v213, v150, v212, v213
	v_fma_f32 v209, v16, v212, v209
	v_fma_f32 v213, v17, v208, v213
	v_fma_f32 v230, v152, v231, v230
	v_fma_f32 v234, v152, v235, v234
	v_fma_f32 v230, v36, v235, v230
	v_fma_f32 v234, v37, v231, v234
	v_cvt_pk_bf16_f32 v135, v209, v213
	v_cvt_pk_bf16_f32 v187, v230, v234
	ds_write2_b32 v193, v132, v135 offset0:136 offset1:204
	ds_write2_b32 v254, v187, v143 offset0:0 offset1:68
	v_fma_f32 v214, v150, v209, v214
	v_fma_f32 v218, v150, v213, v218
	v_fma_f32 v214, v16, v213, v214
	v_fma_f32 v218, v17, v209, v218
	v_fma_f32 v225, v152, v230, v225
	v_fma_f32 v229, v152, v234, v229
	v_fma_f32 v225, v36, v234, v225
	v_fma_f32 v229, v37, v230, v229
	v_cvt_pk_bf16_f32 v128, v214, v218
	v_cvt_pk_bf16_f32 v136, v225, v229
	v_add_u32_e32 v193, 0x34c0, v103
	v_add_u32_e32 v254, 0x3900, v103
	v_fma_f32 v215, v150, v214, v215
	v_fma_f32 v219, v150, v218, v219
	v_fma_f32 v215, v16, v218, v215
	v_fma_f32 v219, v17, v214, v219
	v_fma_f32 v224, v152, v225, v224
	v_fma_f32 v228, v152, v229, v228
	v_fma_f32 v224, v36, v229, v224
	v_fma_f32 v228, v37, v225, v228
	v_cvt_pk_bf16_f32 v131, v215, v219
	v_cvt_pk_bf16_f32 v139, v224, v228
	ds_write2_b32 v193, v128, v131 offset0:0 offset1:68
	ds_write2_b32 v254, v139, v136 offset0:136 offset1:204
	v_fma_f32 v216, v150, v215, v216
	v_fma_f32 v220, v150, v219, v220
	v_fma_f32 v216, v16, v219, v216
	v_fma_f32 v220, v17, v215, v220
	v_fma_f32 v223, v152, v224, v223
	v_fma_f32 v227, v152, v228, v227
	v_fma_f32 v223, v36, v228, v223
	v_fma_f32 v227, v37, v224, v227
	v_cvt_pk_bf16_f32 v132, v216, v220
	v_cvt_pk_bf16_f32 v143, v223, v227
	v_fma_f32 v217, v150, v216, v217
	v_fma_f32 v221, v150, v220, v221
	v_fma_f32 v217, v16, v220, v217
	v_fma_f32 v221, v17, v216, v221
	v_fma_f32 v222, v152, v223, v222
	v_fma_f32 v226, v152, v227, v226
	v_fma_f32 v222, v36, v227, v222
	v_fma_f32 v226, v37, v223, v226
	v_cvt_pk_bf16_f32 v135, v217, v221
	v_cvt_pk_bf16_f32 v187, v222, v226
	ds_write2_b32 v193, v132, v135 offset0:136 offset1:204
	ds_write2_b32 v254, v187, v143 offset0:0 offset1:68
	v_mov_b32_e32 v114, v217
	v_mov_b32_e32 v119, v221
	v_mov_b32_e32 v121, v222
	v_mov_b32_e32 v127, v226
	ds_read_b128 v[188:191], v110 offset:10240
	ds_read_b128 v[194:197], v110 offset:10304
	ds_read_b128 v[198:201], v110 offset:10368
	ds_read_b128 v[202:205], v110 offset:10432
	ds_read_b128 v[206:209], v110 offset:14592
	ds_read_b128 v[210:213], v110 offset:14656
	ds_read_b128 v[214:217], v110 offset:14720
	ds_read_b128 v[218:221], v110 offset:14784
	s_waitcnt lgkmcnt(7)
; #define LAS __attribute__((address_space(3)))
; __device__ __forceinline__ void s5_out_phase(LAS unsigned char* lds, const bf16_t* UZ, const unsigned char* ws, const float* dskip, bf16_t* YG) {
;     ...
;             for (int nt = 0; nt < 8; ++nt) {
;                 const f32x4 z = {0.f, 0.f, 0.f, 0.f};
;                 const f32x4 cf = __builtin_amdgcn_mfma_f32_16x16x16bf16_1k(Uf[mf], Bf[0][nt], z, 0, 0, 0);
;                 const f32x4 cb = __builtin_amdgcn_mfma_f32_16x16x16bf16_1k(Uf[mb], Bf[1][nt], z, 0, 0, 0);
;     ...
;             for (int ks = 0; ks < 4; ++ks) {
;                 const bf16x8 Xf = *(const LAS bf16x8*)(xf + fr * XB_PITCH + (8 * fq + 32 * ks) * 2);
;                 const bf16x8 Xb = *(const LAS bf16x8*)(xbk + fr * XB_PITCH + (8 * fq + 32 * ks) * 2);
;                 accY[mf] = __builtin_amdgcn_mfma_f32_16x16x32_bf16(Cf[0][ks], Xf, accY[mf], 0, 0, 0);
;                 accY[mb] = __builtin_amdgcn_mfma_f32_16x16x32_bf16(Cf[1][ks], Xb, accY[mb], 0, 0, 0);
;             }
	v_mfma_f32_16x16x32_bf16 v[48:51], v[0:3], v[188:191], 0
	s_waitcnt lgkmcnt(3)
	v_mfma_f32_16x16x32_bf16 v[44:47], v[20:23], v[206:209], 0
	v_mfma_f32_16x16x32_bf16 v[48:51], v[4:7], v[194:197], v[48:51]
	s_waitcnt lgkmcnt(2)
	v_mfma_f32_16x16x32_bf16 v[44:47], v[24:27], v[210:213], v[44:47]
	v_mfma_f32_16x16x32_bf16 v[48:51], v[8:11], v[198:201], v[48:51]
	s_waitcnt lgkmcnt(1)
	v_mfma_f32_16x16x32_bf16 v[44:47], v[28:31], v[214:217], v[44:47]
	v_mfma_f32_16x16x32_bf16 v[48:51], v[12:15], v[202:205], v[48:51]
	s_waitcnt lgkmcnt(0)
	v_mfma_f32_16x16x32_bf16 v[44:47], v[32:35], v[218:221], v[44:47]
	s_setprio 2
	v_mfma_f32_4x4x4_16b_bf16 v[188:191], v[170:171], v[60:61], 0 cbsz:4 abid:0
	v_mfma_f32_4x4x4_16b_bf16 v[194:197], v[170:171], v[68:69], 0 cbsz:4 abid:0
	v_mfma_f32_4x4x4_16b_bf16 v[198:201], v[170:171], v[60:61], 0 cbsz:4 abid:1
	v_mfma_f32_4x4x4_16b_bf16 v[202:205], v[170:171], v[68:69], 0 cbsz:4 abid:1
	v_mfma_f32_4x4x4_16b_bf16 v[206:209], v[170:171], v[60:61], 0 cbsz:4 abid:2
	v_mfma_f32_4x4x4_16b_bf16 v[210:213], v[170:171], v[68:69], 0 cbsz:4 abid:2
	v_mfma_f32_4x4x4_16b_bf16 v[214:217], v[170:171], v[60:61], 0 cbsz:4 abid:3
	v_mfma_f32_4x4x4_16b_bf16 v[218:221], v[170:171], v[68:69], 0 cbsz:4 abid:3
	v_mfma_f32_4x4x4_16b_bf16 v[222:225], v[168:169], v[76:77], 0 cbsz:4 abid:0
	v_mfma_f32_4x4x4_16b_bf16 v[226:229], v[168:169], v[84:85], 0 cbsz:4 abid:0
	v_mfma_f32_4x4x4_16b_bf16 v[230:233], v[168:169], v[76:77], 0 cbsz:4 abid:1
	v_mfma_f32_4x4x4_16b_bf16 v[234:237], v[168:169], v[84:85], 0 cbsz:4 abid:1
	v_mfma_f32_4x4x4_16b_bf16 v[238:241], v[168:169], v[76:77], 0 cbsz:4 abid:2
	v_mfma_f32_4x4x4_16b_bf16 v[242:245], v[168:169], v[84:85], 0 cbsz:4 abid:2
	v_mfma_f32_4x4x4_16b_bf16 v[246:249], v[168:169], v[76:77], 0 cbsz:4 abid:3
	v_mfma_f32_4x4x4_16b_bf16 v[250:253], v[168:169], v[84:85], 0 cbsz:4 abid:3
	v_mfma_f32_4x4x4_16b_bf16 v[188:191], v[170:171], v[62:63], v[188:191] cbsz:4 abid:4
	v_mfma_f32_4x4x4_16b_bf16 v[194:197], v[170:171], v[70:71], v[194:197] cbsz:4 abid:4
	v_mfma_f32_4x4x4_16b_bf16 v[198:201], v[170:171], v[62:63], v[198:201] cbsz:4 abid:5
	v_mfma_f32_4x4x4_16b_bf16 v[202:205], v[170:171], v[70:71], v[202:205] cbsz:4 abid:5
	v_mfma_f32_4x4x4_16b_bf16 v[206:209], v[170:171], v[62:63], v[206:209] cbsz:4 abid:6
	v_mfma_f32_4x4x4_16b_bf16 v[210:213], v[170:171], v[70:71], v[210:213] cbsz:4 abid:6
	v_mfma_f32_4x4x4_16b_bf16 v[214:217], v[170:171], v[62:63], v[214:217] cbsz:4 abid:7
	v_mfma_f32_4x4x4_16b_bf16 v[218:221], v[170:171], v[70:71], v[218:221] cbsz:4 abid:7
	v_mfma_f32_4x4x4_16b_bf16 v[222:225], v[168:169], v[78:79], v[222:225] cbsz:4 abid:4
	v_mfma_f32_4x4x4_16b_bf16 v[226:229], v[168:169], v[86:87], v[226:229] cbsz:4 abid:4
	v_mfma_f32_4x4x4_16b_bf16 v[230:233], v[168:169], v[78:79], v[230:233] cbsz:4 abid:5
	v_mfma_f32_4x4x4_16b_bf16 v[234:237], v[168:169], v[86:87], v[234:237] cbsz:4 abid:5
	v_mfma_f32_4x4x4_16b_bf16 v[238:241], v[168:169], v[78:79], v[238:241] cbsz:4 abid:6
	v_mfma_f32_4x4x4_16b_bf16 v[242:245], v[168:169], v[86:87], v[242:245] cbsz:4 abid:6
	v_mfma_f32_4x4x4_16b_bf16 v[246:249], v[168:169], v[78:79], v[246:249] cbsz:4 abid:7
	v_mfma_f32_4x4x4_16b_bf16 v[250:253], v[168:169], v[86:87], v[250:253] cbsz:4 abid:7
	v_mfma_f32_4x4x4_16b_bf16 v[188:191], v[170:171], v[64:65], v[188:191] cbsz:4 abid:8
	v_mfma_f32_4x4x4_16b_bf16 v[194:197], v[170:171], v[72:73], v[194:197] cbsz:4 abid:8
	v_mfma_f32_4x4x4_16b_bf16 v[198:201], v[170:171], v[64:65], v[198:201] cbsz:4 abid:9
	v_mfma_f32_4x4x4_16b_bf16 v[202:205], v[170:171], v[72:73], v[202:205] cbsz:4 abid:9
	v_mfma_f32_4x4x4_16b_bf16 v[206:209], v[170:171], v[64:65], v[206:209] cbsz:4 abid:10
	v_mfma_f32_4x4x4_16b_bf16 v[210:213], v[170:171], v[72:73], v[210:213] cbsz:4 abid:10
	v_mfma_f32_4x4x4_16b_bf16 v[214:217], v[170:171], v[64:65], v[214:217] cbsz:4 abid:11
	v_mfma_f32_4x4x4_16b_bf16 v[218:221], v[170:171], v[72:73], v[218:221] cbsz:4 abid:11
	v_mfma_f32_4x4x4_16b_bf16 v[222:225], v[168:169], v[80:81], v[222:225] cbsz:4 abid:8
	v_mfma_f32_4x4x4_16b_bf16 v[226:229], v[168:169], v[88:89], v[226:229] cbsz:4 abid:8
	v_mfma_f32_4x4x4_16b_bf16 v[230:233], v[168:169], v[80:81], v[230:233] cbsz:4 abid:9
	v_mfma_f32_4x4x4_16b_bf16 v[234:237], v[168:169], v[88:89], v[234:237] cbsz:4 abid:9
	v_mfma_f32_4x4x4_16b_bf16 v[238:241], v[168:169], v[80:81], v[238:241] cbsz:4 abid:10
	v_mfma_f32_4x4x4_16b_bf16 v[242:245], v[168:169], v[88:89], v[242:245] cbsz:4 abid:10
	v_mfma_f32_4x4x4_16b_bf16 v[246:249], v[168:169], v[80:81], v[246:249] cbsz:4 abid:11
	v_mfma_f32_4x4x4_16b_bf16 v[250:253], v[168:169], v[88:89], v[250:253] cbsz:4 abid:11
	v_mfma_f32_4x4x4_16b_bf16 v[188:191], v[170:171], v[66:67], v[188:191] cbsz:4 abid:12
	v_mfma_f32_4x4x4_16b_bf16 v[194:197], v[170:171], v[74:75], v[194:197] cbsz:4 abid:12
	v_mfma_f32_4x4x4_16b_bf16 v[198:201], v[170:171], v[66:67], v[198:201] cbsz:4 abid:13
	v_mfma_f32_4x4x4_16b_bf16 v[202:205], v[170:171], v[74:75], v[202:205] cbsz:4 abid:13
	v_mfma_f32_4x4x4_16b_bf16 v[206:209], v[170:171], v[66:67], v[206:209] cbsz:4 abid:14
	v_mfma_f32_4x4x4_16b_bf16 v[210:213], v[170:171], v[74:75], v[210:213] cbsz:4 abid:14
	v_mfma_f32_4x4x4_16b_bf16 v[214:217], v[170:171], v[66:67], v[214:217] cbsz:4 abid:15
	v_mfma_f32_4x4x4_16b_bf16 v[218:221], v[170:171], v[74:75], v[218:221] cbsz:4 abid:15
	v_mfma_f32_4x4x4_16b_bf16 v[222:225], v[168:169], v[82:83], v[222:225] cbsz:4 abid:12
	v_mfma_f32_4x4x4_16b_bf16 v[226:229], v[168:169], v[90:91], v[226:229] cbsz:4 abid:12
	v_mfma_f32_4x4x4_16b_bf16 v[230:233], v[168:169], v[82:83], v[230:233] cbsz:4 abid:13
	v_mfma_f32_4x4x4_16b_bf16 v[234:237], v[168:169], v[90:91], v[234:237] cbsz:4 abid:13
; #define LAS __attribute__((address_space(3)))
; __device__ __forceinline__ unsigned pk2(float lo, float hi) { f32x2 v = {lo, hi}; nbf2 r = __builtin_convertvector(v, nbf2); return __builtin_bit_cast(unsigned, r); }
; #define WAVE_LDS_FENCE() asm volatile("s_waitcnt lgkmcnt(0)" ::: "memory")
; __device__ __forceinline__ void s5_out_phase(LAS unsigned char* lds, const bf16_t* UZ, const unsigned char* ws, const float* dskip, bf16_t* YG) {
;     ...
;             for (int nt = 0; nt < 8; ++nt) {
;                 const f32x4 z = {0.f, 0.f, 0.f, 0.f};
;                 const f32x4 cf = __builtin_amdgcn_mfma_f32_16x16x16bf16_1k(Uf[mf], Bf[0][nt], z, 0, 0, 0);
;                 const f32x4 cb = __builtin_amdgcn_mfma_f32_16x16x16bf16_1k(Uf[mb], Bf[1][nt], z, 0, 0, 0);
;                 u32x2 wf, wb; wf.x = pk2(cf[0], cf[1]); wf.y = pk2(cf[2], cf[3]); wb.x = pk2(cb[0], cb[1]); wb.y = pk2(cb[2], cb[3]);
;                 *(LAS u32x2*)(wl + nt * 640 + wofs) = wf;
;                 *(LAS u32x2*)(wl + BUT_BYTES + nt * 640 + wofs) = wb;
;             }
;             WAVE_LDS_FENCE();
;             const LAS unsigned char* rp = wl + lane * 80;
;             const u32x4 fre0 = *(const LAS u32x4*)(rp), fre1 = *(const LAS u32x4*)(rp + 16), fim0 = *(const LAS u32x4*)(rp + 32), fim1 = *(const LAS u32x4*)(rp + 48);
;             const u32x4 bre0 = *(const LAS u32x4*)(rp + BUT_BYTES), bre1 = *(const LAS u32x4*)(rp + BUT_BYTES + 16), bim0 = *(const LAS u32x4*)(rp + BUT_BYTES + 32), bim1 = *(const LAS u32x4*)(rp + BUT_BYTES + 48);
;             LAS unsigned char* xf = wl + 2 * BUT_BYTES; LAS unsigned char* xbk = xf + XB_BYTES;
; #pragma unroll
;             for (int rr = 0; rr < 16; ++rr) {
;                 const int r = rr, rb = 15 - rr;
;                 { const f32x2 bb = {bf_at(fre0, fre1, r), bf_at(fim0, fim1, r)};
;                   const f32x2 n2 = cmac((f32x2){xfr, xfi}, (f32x2){ap[0].x, ap[0].x}, (f32x2){-ap[0].y, ap[0].y}, bb); xfr = n2.x; xfi = n2.y;
;                   *(LAS unsigned*)(xf + r * XB_PITCH + lane * 4) = pk2(n2.x, n2.y); }
;                 { const f32x2 bb = {bf_at(bre0, bre1, rb), bf_at(bim0, bim1, rb)};
;                   const f32x2 n2 = cmac((f32x2){xbr, xbi}, (f32x2){ap[1].x, ap[1].x}, (f32x2){-ap[1].y, ap[1].y}, bb); xbr = n2.x; xbi = n2.y;
;                   *(LAS unsigned*)(xbk + rb * XB_PITCH + lane * 4) = pk2(n2.x, n2.y); }
;             }
	v_mfma_f32_4x4x4_16b_bf16 v[238:241], v[168:169], v[82:83], v[238:241] cbsz:4 abid:14
	v_mfma_f32_4x4x4_16b_bf16 v[242:245], v[168:169], v[90:91], v[242:245] cbsz:4 abid:14
	v_mfma_f32_4x4x4_16b_bf16 v[246:249], v[168:169], v[82:83], v[246:249] cbsz:4 abid:15
	v_mfma_f32_4x4x4_16b_bf16 v[250:253], v[168:169], v[90:91], v[250:253] cbsz:4 abid:15
	s_setprio 0
	v_fma_f32 v188, v150, v114, v188
	v_fma_f32 v194, v150, v119, v194
	v_fma_f32 v188, v16, v119, v188
	v_fma_f32 v194, v17, v114, v194
	v_fma_f32 v249, v152, v121, v249
	v_fma_f32 v253, v152, v127, v253
	v_fma_f32 v249, v36, v127, v249
	v_fma_f32 v253, v37, v121, v253
	v_cvt_pk_bf16_f32 v128, v188, v194
	v_cvt_pk_bf16_f32 v136, v249, v253
	v_add_u32_e32 v193, 0x2800, v103
	v_add_u32_e32 v254, 0x45c0, v103
	v_fma_f32 v189, v150, v188, v189
	v_fma_f32 v195, v150, v194, v195
	v_fma_f32 v189, v16, v194, v189
	v_fma_f32 v195, v17, v188, v195
	v_fma_f32 v248, v152, v249, v248
	v_fma_f32 v252, v152, v253, v252
	v_fma_f32 v248, v36, v253, v248
	v_fma_f32 v252, v37, v249, v252
	v_cvt_pk_bf16_f32 v131, v189, v195
	v_cvt_pk_bf16_f32 v139, v248, v252
	ds_write2_b32 v193, v128, v131 offset0:0 offset1:68
	ds_write2_b32 v254, v139, v136 offset0:136 offset1:204
	v_fma_f32 v190, v150, v189, v190
	v_fma_f32 v196, v150, v195, v196
	v_fma_f32 v190, v16, v195, v190
	v_fma_f32 v196, v17, v189, v196
	v_fma_f32 v247, v152, v248, v247
	v_fma_f32 v251, v152, v252, v251
	v_fma_f32 v247, v36, v252, v247
	v_fma_f32 v251, v37, v248, v251
	v_cvt_pk_bf16_f32 v132, v190, v196
	v_cvt_pk_bf16_f32 v143, v247, v251
	v_fma_f32 v191, v150, v190, v191
	v_fma_f32 v197, v150, v196, v197
	v_fma_f32 v191, v16, v196, v191
	v_fma_f32 v197, v17, v190, v197
	v_fma_f32 v246, v152, v247, v246
	v_fma_f32 v250, v152, v251, v250
	v_fma_f32 v246, v36, v251, v246
	v_fma_f32 v250, v37, v247, v250
	v_cvt_pk_bf16_f32 v135, v191, v197
	v_cvt_pk_bf16_f32 v187, v246, v250
	ds_write2_b32 v193, v132, v135 offset0:136 offset1:204
	ds_write2_b32 v254, v187, v143 offset0:0 offset1:68
	v_fma_f32 v198, v150, v191, v198
	v_fma_f32 v202, v150, v197, v202
	v_fma_f32 v198, v16, v197, v198
	v_fma_f32 v202, v17, v191, v202
	v_fma_f32 v241, v152, v246, v241
	v_fma_f32 v245, v152, v250, v245
	v_fma_f32 v241, v36, v250, v241
	v_fma_f32 v245, v37, v246, v245
	v_cvt_pk_bf16_f32 v128, v198, v202
	v_cvt_pk_bf16_f32 v136, v241, v245
	v_add_u32_e32 v193, 0x2c40, v103
	v_add_u32_e32 v254, 0x4180, v103
	v_fma_f32 v199, v150, v198, v199
	v_fma_f32 v203, v150, v202, v203
	v_fma_f32 v199, v16, v202, v199
	v_fma_f32 v203, v17, v198, v203
	v_fma_f32 v240, v152, v241, v240
	v_fma_f32 v244, v152, v245, v244
	v_fma_f32 v240, v36, v245, v240
	v_fma_f32 v244, v37, v241, v244
	v_cvt_pk_bf16_f32 v131, v199, v203
	v_cvt_pk_bf16_f32 v139, v240, v244
	ds_write2_b32 v193, v128, v131 offset0:0 offset1:68
	ds_write2_b32 v254, v139, v136 offset0:136 offset1:204
	v_fma_f32 v200, v150, v199, v200
	v_fma_f32 v204, v150, v203, v204
	v_fma_f32 v200, v16, v203, v200
	v_fma_f32 v204, v17, v199, v204
	v_fma_f32 v239, v152, v240, v239
	v_fma_f32 v243, v152, v244, v243
	v_fma_f32 v239, v36, v244, v239
	v_fma_f32 v243, v37, v240, v243
	v_cvt_pk_bf16_f32 v132, v200, v204
	v_cvt_pk_bf16_f32 v143, v239, v243
	v_fma_f32 v201, v150, v200, v201
	v_fma_f32 v205, v150, v204, v205
	v_fma_f32 v201, v16, v204, v201
	v_fma_f32 v205, v17, v200, v205
	v_fma_f32 v238, v152, v239, v238
	v_fma_f32 v242, v152, v243, v242
	v_fma_f32 v238, v36, v243, v238
	v_fma_f32 v242, v37, v239, v242
	v_cvt_pk_bf16_f32 v135, v201, v205
	v_cvt_pk_bf16_f32 v187, v238, v242
	ds_write2_b32 v193, v132, v135 offset0:136 offset1:204
	ds_write2_b32 v254, v187, v143 offset0:0 offset1:68
	v_fma_f32 v206, v150, v201, v206
	v_fma_f32 v210, v150, v205, v210
	v_fma_f32 v206, v16, v205, v206
	v_fma_f32 v210, v17, v201, v210
	v_fma_f32 v233, v152, v238, v233
	v_fma_f32 v237, v152, v242, v237
	v_fma_f32 v233, v36, v242, v233
	v_fma_f32 v237, v37, v238, v237
	v_cvt_pk_bf16_f32 v128, v206, v210
	v_cvt_pk_bf16_f32 v136, v233, v237
	v_add_u32_e32 v193, 0x3080, v103
	v_add_u32_e32 v254, 0x3d40, v103
	v_fma_f32 v207, v150, v206, v207
	v_fma_f32 v211, v150, v210, v211
	v_fma_f32 v207, v16, v210, v207
	v_fma_f32 v211, v17, v206, v211
	v_fma_f32 v232, v152, v233, v232
	v_fma_f32 v236, v152, v237, v236
	v_fma_f32 v232, v36, v237, v232
	v_fma_f32 v236, v37, v233, v236
	v_cvt_pk_bf16_f32 v131, v207, v211
	v_cvt_pk_bf16_f32 v139, v232, v236
	ds_write2_b32 v193, v128, v131 offset0:0 offset1:68
	ds_write2_b32 v254, v139, v136 offset0:136 offset1:204
	v_fma_f32 v208, v150, v207, v208
	v_fma_f32 v212, v150, v211, v212
	v_fma_f32 v208, v16, v211, v208
	v_fma_f32 v212, v17, v207, v212
	v_fma_f32 v231, v152, v232, v231
	v_fma_f32 v235, v152, v236, v235
	v_fma_f32 v231, v36, v236, v231
	v_fma_f32 v235, v37, v232, v235
	v_cvt_pk_bf16_f32 v132, v208, v212
	v_cvt_pk_bf16_f32 v143, v231, v235
	v_fma_f32 v209, v150, v208, v209
	v_fma_f32 v213, v150, v212, v213
	v_fma_f32 v209, v16, v212, v209
	v_fma_f32 v213, v17, v208, v213
	v_fma_f32 v230, v152, v231, v230
	v_fma_f32 v234, v152, v235, v234
	v_fma_f32 v230, v36, v235, v230
	v_fma_f32 v234, v37, v231, v234
	v_cvt_pk_bf16_f32 v135, v209, v213
	v_cvt_pk_bf16_f32 v187, v230, v234
	ds_write2_b32 v193, v132, v135 offset0:136 offset1:204
	ds_write2_b32 v254, v187, v143 offset0:0 offset1:68
	v_fma_f32 v214, v150, v209, v214
	v_fma_f32 v218, v150, v213, v218
	v_fma_f32 v214, v16, v213, v214
	v_fma_f32 v218, v17, v209, v218
	v_fma_f32 v225, v152, v230, v225
	v_fma_f32 v229, v152, v234, v229
	v_fma_f32 v225, v36, v234, v225
	v_fma_f32 v229, v37, v230, v229
	v_cvt_pk_bf16_f32 v128, v214, v218
	v_cvt_pk_bf16_f32 v136, v225, v229
; #define LAS __attribute__((address_space(3)))
; __device__ __forceinline__ unsigned pk2(float lo, float hi) { f32x2 v = {lo, hi}; nbf2 r = __builtin_convertvector(v, nbf2); return __builtin_bit_cast(unsigned, r); }
; #define WAVE_LDS_FENCE() asm volatile("s_waitcnt lgkmcnt(0)" ::: "memory")
; __device__ __forceinline__ float bf_at(const u32x4& lo, const u32x4& hi, int r) { const unsigned w = (r < 8 ? lo : hi)[(r & 7) >> 1]; return (r & 1) ? bf_hi(w) : bf_lo(w); }
; __device__ __forceinline__ void s5_out_phase(LAS unsigned char* lds, const bf16_t* UZ, const unsigned char* ws, const float* dskip, bf16_t* YG) {
;     ...
;             for (int nt = 0; nt < 8; ++nt) {
;                 const f32x4 z = {0.f, 0.f, 0.f, 0.f};
;                 const f32x4 cf = __builtin_amdgcn_mfma_f32_16x16x16bf16_1k(Uf[mf], Bf[0][nt], z, 0, 0, 0);
;                 const f32x4 cb = __builtin_amdgcn_mfma_f32_16x16x16bf16_1k(Uf[mb], Bf[1][nt], z, 0, 0, 0);
;     ...
; #pragma unroll
;             for (int rr = 0; rr < 16; ++rr) {
;                 const int r = rr, rb = 15 - rr;
;                 { const f32x2 bb = {bf_at(fre0, fre1, r), bf_at(fim0, fim1, r)};
;                   const f32x2 n2 = cmac((f32x2){xfr, xfi}, (f32x2){ap[0].x, ap[0].x}, (f32x2){-ap[0].y, ap[0].y}, bb); xfr = n2.x; xfi = n2.y;
;                   *(LAS unsigned*)(xf + r * XB_PITCH + lane * 4) = pk2(n2.x, n2.y); }
;                 { const f32x2 bb = {bf_at(bre0, bre1, rb), bf_at(bim0, bim1, rb)};
;                   const f32x2 n2 = cmac((f32x2){xbr, xbi}, (f32x2){ap[1].x, ap[1].x}, (f32x2){-ap[1].y, ap[1].y}, bb); xbr = n2.x; xbi = n2.y;
;                   *(LAS unsigned*)(xbk + rb * XB_PITCH + lane * 4) = pk2(n2.x, n2.y); }
;             }
;             WAVE_LDS_FENCE();
; #pragma unroll
;             for (int ks = 0; ks < 4; ++ks) {
;                 const bf16x8 Xf = *(const LAS bf16x8*)(xf + fr * XB_PITCH + (8 * fq + 32 * ks) * 2);
;                 const bf16x8 Xb = *(const LAS bf16x8*)(xbk + fr * XB_PITCH + (8 * fq + 32 * ks) * 2);
;                 accY[mf] = __builtin_amdgcn_mfma_f32_16x16x32_bf16(Cf[0][ks], Xf, accY[mf], 0, 0, 0);
;                 accY[mb] = __builtin_amdgcn_mfma_f32_16x16x32_bf16(Cf[1][ks], Xb, accY[mb], 0, 0, 0);
;             }
	v_add_u32_e32 v193, 0x34c0, v103
	v_add_u32_e32 v254, 0x3900, v103
	v_fma_f32 v215, v150, v214, v215
	v_fma_f32 v219, v150, v218, v219
	v_fma_f32 v215, v16, v218, v215
	v_fma_f32 v219, v17, v214, v219
	v_fma_f32 v224, v152, v225, v224
	v_fma_f32 v228, v152, v229, v228
	v_fma_f32 v224, v36, v229, v224
	v_fma_f32 v228, v37, v225, v228
	v_cvt_pk_bf16_f32 v131, v215, v219
	v_cvt_pk_bf16_f32 v139, v224, v228
	ds_write2_b32 v193, v128, v131 offset0:0 offset1:68
	ds_write2_b32 v254, v139, v136 offset0:136 offset1:204
	v_fma_f32 v216, v150, v215, v216
	v_fma_f32 v220, v150, v219, v220
	v_fma_f32 v216, v16, v219, v216
	v_fma_f32 v220, v17, v215, v220
	v_fma_f32 v223, v152, v224, v223
	v_fma_f32 v227, v152, v228, v227
	v_fma_f32 v223, v36, v228, v223
	v_fma_f32 v227, v37, v224, v227
	v_cvt_pk_bf16_f32 v132, v216, v220
	v_cvt_pk_bf16_f32 v143, v223, v227
	v_fma_f32 v217, v150, v216, v217
	v_fma_f32 v221, v150, v220, v221
	v_fma_f32 v217, v16, v220, v217
	v_fma_f32 v221, v17, v216, v221
	v_fma_f32 v222, v152, v223, v222
	v_fma_f32 v226, v152, v227, v226
	v_fma_f32 v222, v36, v227, v222
	v_fma_f32 v226, v37, v223, v226
	v_cvt_pk_bf16_f32 v135, v217, v221
	v_cvt_pk_bf16_f32 v187, v222, v226
	ds_write2_b32 v193, v132, v135 offset0:136 offset1:204
	ds_write2_b32 v254, v187, v143 offset0:0 offset1:68
	v_mov_b32_e32 v114, v217
	v_mov_b32_e32 v119, v221
	v_mov_b32_e32 v121, v222
	v_mov_b32_e32 v127, v226
	ds_read_b128 v[188:191], v110 offset:10240
	ds_read_b128 v[194:197], v110 offset:10304
	ds_read_b128 v[198:201], v110 offset:10368
	ds_read_b128 v[202:205], v110 offset:10432
	ds_read_b128 v[206:209], v110 offset:14592
	ds_read_b128 v[210:213], v110 offset:14656
	ds_read_b128 v[214:217], v110 offset:14720
	ds_read_b128 v[218:221], v110 offset:14784
	s_waitcnt lgkmcnt(7)
	v_mfma_f32_16x16x32_bf16 v[56:59], v[0:3], v[188:191], 0
	s_waitcnt lgkmcnt(3)
	v_mfma_f32_16x16x32_bf16 v[52:55], v[20:23], v[206:209], 0
	v_mfma_f32_16x16x32_bf16 v[56:59], v[4:7], v[194:197], v[56:59]
	s_waitcnt lgkmcnt(2)
	v_mfma_f32_16x16x32_bf16 v[52:55], v[24:27], v[210:213], v[52:55]
	v_mfma_f32_16x16x32_bf16 v[56:59], v[8:11], v[198:201], v[56:59]
	s_waitcnt lgkmcnt(1)
	v_mfma_f32_16x16x32_bf16 v[52:55], v[28:31], v[214:217], v[52:55]
	v_mfma_f32_16x16x32_bf16 v[56:59], v[12:15], v[202:205], v[56:59]
	s_waitcnt lgkmcnt(0)
	v_mfma_f32_16x16x32_bf16 v[52:55], v[32:35], v[218:221], v[52:55]
	s_setprio 2
	v_mfma_f32_4x4x4_16b_bf16 v[188:191], v[168:169], v[60:61], 0 cbsz:4 abid:0
	v_mfma_f32_4x4x4_16b_bf16 v[194:197], v[168:169], v[68:69], 0 cbsz:4 abid:0
	v_mfma_f32_4x4x4_16b_bf16 v[198:201], v[168:169], v[60:61], 0 cbsz:4 abid:1
	v_mfma_f32_4x4x4_16b_bf16 v[202:205], v[168:169], v[68:69], 0 cbsz:4 abid:1
	v_mfma_f32_4x4x4_16b_bf16 v[206:209], v[168:169], v[60:61], 0 cbsz:4 abid:2
	v_mfma_f32_4x4x4_16b_bf16 v[210:213], v[168:169], v[68:69], 0 cbsz:4 abid:2
	v_mfma_f32_4x4x4_16b_bf16 v[214:217], v[168:169], v[60:61], 0 cbsz:4 abid:3
	v_mfma_f32_4x4x4_16b_bf16 v[218:221], v[168:169], v[68:69], 0 cbsz:4 abid:3
	v_mfma_f32_4x4x4_16b_bf16 v[222:225], v[170:171], v[76:77], 0 cbsz:4 abid:0
	v_mfma_f32_4x4x4_16b_bf16 v[226:229], v[170:171], v[84:85], 0 cbsz:4 abid:0
	v_mfma_f32_4x4x4_16b_bf16 v[230:233], v[170:171], v[76:77], 0 cbsz:4 abid:1
	v_mfma_f32_4x4x4_16b_bf16 v[234:237], v[170:171], v[84:85], 0 cbsz:4 abid:1
	v_mfma_f32_4x4x4_16b_bf16 v[238:241], v[170:171], v[76:77], 0 cbsz:4 abid:2
	v_mfma_f32_4x4x4_16b_bf16 v[242:245], v[170:171], v[84:85], 0 cbsz:4 abid:2
	v_mfma_f32_4x4x4_16b_bf16 v[246:249], v[170:171], v[76:77], 0 cbsz:4 abid:3
	v_mfma_f32_4x4x4_16b_bf16 v[250:253], v[170:171], v[84:85], 0 cbsz:4 abid:3
	v_mfma_f32_4x4x4_16b_bf16 v[188:191], v[168:169], v[62:63], v[188:191] cbsz:4 abid:4
	v_mfma_f32_4x4x4_16b_bf16 v[194:197], v[168:169], v[70:71], v[194:197] cbsz:4 abid:4
	v_mfma_f32_4x4x4_16b_bf16 v[198:201], v[168:169], v[62:63], v[198:201] cbsz:4 abid:5
	v_mfma_f32_4x4x4_16b_bf16 v[202:205], v[168:169], v[70:71], v[202:205] cbsz:4 abid:5
	v_mfma_f32_4x4x4_16b_bf16 v[206:209], v[168:169], v[62:63], v[206:209] cbsz:4 abid:6
	v_mfma_f32_4x4x4_16b_bf16 v[210:213], v[168:169], v[70:71], v[210:213] cbsz:4 abid:6
	v_mfma_f32_4x4x4_16b_bf16 v[214:217], v[168:169], v[62:63], v[214:217] cbsz:4 abid:7
	v_mfma_f32_4x4x4_16b_bf16 v[218:221], v[168:169], v[70:71], v[218:221] cbsz:4 abid:7
	v_mfma_f32_4x4x4_16b_bf16 v[222:225], v[170:171], v[78:79], v[222:225] cbsz:4 abid:4
	v_mfma_f32_4x4x4_16b_bf16 v[226:229], v[170:171], v[86:87], v[226:229] cbsz:4 abid:4
	v_mfma_f32_4x4x4_16b_bf16 v[230:233], v[170:171], v[78:79], v[230:233] cbsz:4 abid:5
	v_mfma_f32_4x4x4_16b_bf16 v[234:237], v[170:171], v[86:87], v[234:237] cbsz:4 abid:5
	v_mfma_f32_4x4x4_16b_bf16 v[238:241], v[170:171], v[78:79], v[238:241] cbsz:4 abid:6
	v_mfma_f32_4x4x4_16b_bf16 v[242:245], v[170:171], v[86:87], v[242:245] cbsz:4 abid:6
	v_mfma_f32_4x4x4_16b_bf16 v[246:249], v[170:171], v[78:79], v[246:249] cbsz:4 abid:7
	v_mfma_f32_4x4x4_16b_bf16 v[250:253], v[170:171], v[86:87], v[250:253] cbsz:4 abid:7
	v_mfma_f32_4x4x4_16b_bf16 v[188:191], v[168:169], v[64:65], v[188:191] cbsz:4 abid:8
	v_mfma_f32_4x4x4_16b_bf16 v[194:197], v[168:169], v[72:73], v[194:197] cbsz:4 abid:8
	v_mfma_f32_4x4x4_16b_bf16 v[198:201], v[168:169], v[64:65], v[198:201] cbsz:4 abid:9
	v_mfma_f32_4x4x4_16b_bf16 v[202:205], v[168:169], v[72:73], v[202:205] cbsz:4 abid:9
	v_mfma_f32_4x4x4_16b_bf16 v[206:209], v[168:169], v[64:65], v[206:209] cbsz:4 abid:10
	v_mfma_f32_4x4x4_16b_bf16 v[210:213], v[168:169], v[72:73], v[210:213] cbsz:4 abid:10
	v_mfma_f32_4x4x4_16b_bf16 v[214:217], v[168:169], v[64:65], v[214:217] cbsz:4 abid:11
; #define LAS __attribute__((address_space(3)))
; __device__ __forceinline__ unsigned pk2(float lo, float hi) { f32x2 v = {lo, hi}; nbf2 r = __builtin_convertvector(v, nbf2); return __builtin_bit_cast(unsigned, r); }
; #define WAVE_LDS_FENCE() asm volatile("s_waitcnt lgkmcnt(0)" ::: "memory")
; __device__ __forceinline__ void s5_out_phase(LAS unsigned char* lds, const bf16_t* UZ, const unsigned char* ws, const float* dskip, bf16_t* YG) {
;     ...
;             for (int nt = 0; nt < 8; ++nt) {
;                 const f32x4 z = {0.f, 0.f, 0.f, 0.f};
;                 const f32x4 cf = __builtin_amdgcn_mfma_f32_16x16x16bf16_1k(Uf[mf], Bf[0][nt], z, 0, 0, 0);
;                 const f32x4 cb = __builtin_amdgcn_mfma_f32_16x16x16bf16_1k(Uf[mb], Bf[1][nt], z, 0, 0, 0);
;                 u32x2 wf, wb; wf.x = pk2(cf[0], cf[1]); wf.y = pk2(cf[2], cf[3]); wb.x = pk2(cb[0], cb[1]); wb.y = pk2(cb[2], cb[3]);
;                 *(LAS u32x2*)(wl + nt * 640 + wofs) = wf;
;                 *(LAS u32x2*)(wl + BUT_BYTES + nt * 640 + wofs) = wb;
;             }
;             WAVE_LDS_FENCE();
;             const LAS unsigned char* rp = wl + lane * 80;
;             const u32x4 fre0 = *(const LAS u32x4*)(rp), fre1 = *(const LAS u32x4*)(rp + 16), fim0 = *(const LAS u32x4*)(rp + 32), fim1 = *(const LAS u32x4*)(rp + 48);
;             const u32x4 bre0 = *(const LAS u32x4*)(rp + BUT_BYTES), bre1 = *(const LAS u32x4*)(rp + BUT_BYTES + 16), bim0 = *(const LAS u32x4*)(rp + BUT_BYTES + 32), bim1 = *(const LAS u32x4*)(rp + BUT_BYTES + 48);
;             LAS unsigned char* xf = wl + 2 * BUT_BYTES; LAS unsigned char* xbk = xf + XB_BYTES;
; #pragma unroll
;             for (int rr = 0; rr < 16; ++rr) {
;                 const int r = rr, rb = 15 - rr;
;                 { const f32x2 bb = {bf_at(fre0, fre1, r), bf_at(fim0, fim1, r)};
;                   const f32x2 n2 = cmac((f32x2){xfr, xfi}, (f32x2){ap[0].x, ap[0].x}, (f32x2){-ap[0].y, ap[0].y}, bb); xfr = n2.x; xfi = n2.y;
;                   *(LAS unsigned*)(xf + r * XB_PITCH + lane * 4) = pk2(n2.x, n2.y); }
;                 { const f32x2 bb = {bf_at(bre0, bre1, rb), bf_at(bim0, bim1, rb)};
;                   const f32x2 n2 = cmac((f32x2){xbr, xbi}, (f32x2){ap[1].x, ap[1].x}, (f32x2){-ap[1].y, ap[1].y}, bb); xbr = n2.x; xbi = n2.y;
;                   *(LAS unsigned*)(xbk + rb * XB_PITCH + lane * 4) = pk2(n2.x, n2.y); }
;             }
	v_mfma_f32_4x4x4_16b_bf16 v[218:221], v[168:169], v[72:73], v[218:221] cbsz:4 abid:11
	v_mfma_f32_4x4x4_16b_bf16 v[222:225], v[170:171], v[80:81], v[222:225] cbsz:4 abid:8
	v_mfma_f32_4x4x4_16b_bf16 v[226:229], v[170:171], v[88:89], v[226:229] cbsz:4 abid:8
	v_mfma_f32_4x4x4_16b_bf16 v[230:233], v[170:171], v[80:81], v[230:233] cbsz:4 abid:9
	v_mfma_f32_4x4x4_16b_bf16 v[234:237], v[170:171], v[88:89], v[234:237] cbsz:4 abid:9
	v_mfma_f32_4x4x4_16b_bf16 v[238:241], v[170:171], v[80:81], v[238:241] cbsz:4 abid:10
	v_mfma_f32_4x4x4_16b_bf16 v[242:245], v[170:171], v[88:89], v[242:245] cbsz:4 abid:10
	v_mfma_f32_4x4x4_16b_bf16 v[246:249], v[170:171], v[80:81], v[246:249] cbsz:4 abid:11
	v_mfma_f32_4x4x4_16b_bf16 v[250:253], v[170:171], v[88:89], v[250:253] cbsz:4 abid:11
	v_mfma_f32_4x4x4_16b_bf16 v[188:191], v[168:169], v[66:67], v[188:191] cbsz:4 abid:12
	v_mfma_f32_4x4x4_16b_bf16 v[194:197], v[168:169], v[74:75], v[194:197] cbsz:4 abid:12
	v_mfma_f32_4x4x4_16b_bf16 v[198:201], v[168:169], v[66:67], v[198:201] cbsz:4 abid:13
	v_mfma_f32_4x4x4_16b_bf16 v[202:205], v[168:169], v[74:75], v[202:205] cbsz:4 abid:13
	v_mfma_f32_4x4x4_16b_bf16 v[206:209], v[168:169], v[66:67], v[206:209] cbsz:4 abid:14
	v_mfma_f32_4x4x4_16b_bf16 v[210:213], v[168:169], v[74:75], v[210:213] cbsz:4 abid:14
	v_mfma_f32_4x4x4_16b_bf16 v[214:217], v[168:169], v[66:67], v[214:217] cbsz:4 abid:15
	v_mfma_f32_4x4x4_16b_bf16 v[218:221], v[168:169], v[74:75], v[218:221] cbsz:4 abid:15
	v_mfma_f32_4x4x4_16b_bf16 v[222:225], v[170:171], v[82:83], v[222:225] cbsz:4 abid:12
	v_mfma_f32_4x4x4_16b_bf16 v[226:229], v[170:171], v[90:91], v[226:229] cbsz:4 abid:12
	v_mfma_f32_4x4x4_16b_bf16 v[230:233], v[170:171], v[82:83], v[230:233] cbsz:4 abid:13
	v_mfma_f32_4x4x4_16b_bf16 v[234:237], v[170:171], v[90:91], v[234:237] cbsz:4 abid:13
	v_mfma_f32_4x4x4_16b_bf16 v[238:241], v[170:171], v[82:83], v[238:241] cbsz:4 abid:14
	v_mfma_f32_4x4x4_16b_bf16 v[242:245], v[170:171], v[90:91], v[242:245] cbsz:4 abid:14
	v_mfma_f32_4x4x4_16b_bf16 v[246:249], v[170:171], v[82:83], v[246:249] cbsz:4 abid:15
	v_mfma_f32_4x4x4_16b_bf16 v[250:253], v[170:171], v[90:91], v[250:253] cbsz:4 abid:15
	s_setprio 0
	v_fma_f32 v188, v150, v114, v188
	v_fma_f32 v194, v150, v119, v194
	v_fma_f32 v188, v16, v119, v188
	v_fma_f32 v194, v17, v114, v194
	v_fma_f32 v249, v152, v121, v249
	v_fma_f32 v253, v152, v127, v253
	v_fma_f32 v249, v36, v127, v249
	v_fma_f32 v253, v37, v121, v253
	v_cvt_pk_bf16_f32 v128, v188, v194
	v_cvt_pk_bf16_f32 v136, v249, v253
	v_add_u32_e32 v193, 0x2800, v103
	v_add_u32_e32 v254, 0x45c0, v103
	v_fma_f32 v189, v150, v188, v189
	v_fma_f32 v195, v150, v194, v195
	v_fma_f32 v189, v16, v194, v189
	v_fma_f32 v195, v17, v188, v195
	v_fma_f32 v248, v152, v249, v248
	v_fma_f32 v252, v152, v253, v252
	v_fma_f32 v248, v36, v253, v248
	v_fma_f32 v252, v37, v249, v252
	v_cvt_pk_bf16_f32 v131, v189, v195
	v_cvt_pk_bf16_f32 v139, v248, v252
	ds_write2_b32 v193, v128, v131 offset0:0 offset1:68
	ds_write2_b32 v254, v139, v136 offset0:136 offset1:204
	v_fma_f32 v190, v150, v189, v190
	v_fma_f32 v196, v150, v195, v196
	v_fma_f32 v190, v16, v195, v190
	v_fma_f32 v196, v17, v189, v196
	v_fma_f32 v247, v152, v248, v247
	v_fma_f32 v251, v152, v252, v251
	v_fma_f32 v247, v36, v252, v247
	v_fma_f32 v251, v37, v248, v251
	v_cvt_pk_bf16_f32 v132, v190, v196
	v_cvt_pk_bf16_f32 v143, v247, v251
	v_fma_f32 v191, v150, v190, v191
	v_fma_f32 v197, v150, v196, v197
	v_fma_f32 v191, v16, v196, v191
	v_fma_f32 v197, v17, v190, v197
	v_fma_f32 v246, v152, v247, v246
	v_fma_f32 v250, v152, v251, v250
	v_fma_f32 v246, v36, v251, v246
	v_fma_f32 v250, v37, v247, v250
	v_cvt_pk_bf16_f32 v135, v191, v197
	v_cvt_pk_bf16_f32 v187, v246, v250
	ds_write2_b32 v193, v132, v135 offset0:136 offset1:204
	ds_write2_b32 v254, v187, v143 offset0:0 offset1:68
	v_fma_f32 v198, v150, v191, v198
	v_fma_f32 v202, v150, v197, v202
	v_fma_f32 v198, v16, v197, v198
	v_fma_f32 v202, v17, v191, v202
	v_fma_f32 v241, v152, v246, v241
	v_fma_f32 v245, v152, v250, v245
	v_fma_f32 v241, v36, v250, v241
	v_fma_f32 v245, v37, v246, v245
	v_cvt_pk_bf16_f32 v128, v198, v202
	v_cvt_pk_bf16_f32 v136, v241, v245
	v_add_u32_e32 v193, 0x2c40, v103
	v_add_u32_e32 v254, 0x4180, v103
	v_fma_f32 v199, v150, v198, v199
	v_fma_f32 v203, v150, v202, v203
	v_fma_f32 v199, v16, v202, v199
	v_fma_f32 v203, v17, v198, v203
	v_fma_f32 v240, v152, v241, v240
	v_fma_f32 v244, v152, v245, v244
	v_fma_f32 v240, v36, v245, v240
	v_fma_f32 v244, v37, v241, v244
	v_cvt_pk_bf16_f32 v131, v199, v203
	v_cvt_pk_bf16_f32 v139, v240, v244
	ds_write2_b32 v193, v128, v131 offset0:0 offset1:68
	ds_write2_b32 v254, v139, v136 offset0:136 offset1:204
	v_fma_f32 v200, v150, v199, v200
	v_fma_f32 v204, v150, v203, v204
	v_fma_f32 v200, v16, v203, v200
	v_fma_f32 v204, v17, v199, v204
	v_fma_f32 v239, v152, v240, v239
	v_fma_f32 v243, v152, v244, v243
	v_fma_f32 v239, v36, v244, v239
	v_fma_f32 v243, v37, v240, v243
	v_cvt_pk_bf16_f32 v132, v200, v204
	v_cvt_pk_bf16_f32 v143, v239, v243
	v_fma_f32 v201, v150, v200, v201
	v_fma_f32 v205, v150, v204, v205
	v_fma_f32 v201, v16, v204, v201
	v_fma_f32 v205, v17, v200, v205
	v_fma_f32 v238, v152, v239, v238
	v_fma_f32 v242, v152, v243, v242
	v_fma_f32 v238, v36, v243, v238
	v_fma_f32 v242, v37, v239, v242
	v_cvt_pk_bf16_f32 v135, v201, v205
	v_cvt_pk_bf16_f32 v187, v238, v242
	ds_write2_b32 v193, v132, v135 offset0:136 offset1:204
	ds_write2_b32 v254, v187, v143 offset0:0 offset1:68
	v_fma_f32 v206, v150, v201, v206
	v_fma_f32 v210, v150, v205, v210
	v_fma_f32 v206, v16, v205, v206
	v_fma_f32 v210, v17, v201, v210
	v_fma_f32 v233, v152, v238, v233
; #define LAS __attribute__((address_space(3)))
; __device__ __forceinline__ unsigned pk2(float lo, float hi) { f32x2 v = {lo, hi}; nbf2 r = __builtin_convertvector(v, nbf2); return __builtin_bit_cast(unsigned, r); }
; #define WAVE_LDS_FENCE() asm volatile("s_waitcnt lgkmcnt(0)" ::: "memory")
; __device__ __forceinline__ float bf_at(const u32x4& lo, const u32x4& hi, int r) { const unsigned w = (r < 8 ? lo : hi)[(r & 7) >> 1]; return (r & 1) ? bf_hi(w) : bf_lo(w); }
; __device__ __forceinline__ void s5_out_phase(LAS unsigned char* lds, const bf16_t* UZ, const unsigned char* ws, const float* dskip, bf16_t* YG) {
;     ...
;             for (int nt = 0; nt < 8; ++nt) {
;                 const f32x4 z = {0.f, 0.f, 0.f, 0.f};
;                 const f32x4 cf = __builtin_amdgcn_mfma_f32_16x16x16bf16_1k(Uf[mf], Bf[0][nt], z, 0, 0, 0);
;                 const f32x4 cb = __builtin_amdgcn_mfma_f32_16x16x16bf16_1k(Uf[mb], Bf[1][nt], z, 0, 0, 0);
;     ...
; #pragma unroll
;             for (int rr = 0; rr < 16; ++rr) {
;                 const int r = rr, rb = 15 - rr;
;                 { const f32x2 bb = {bf_at(fre0, fre1, r), bf_at(fim0, fim1, r)};
;                   const f32x2 n2 = cmac((f32x2){xfr, xfi}, (f32x2){ap[0].x, ap[0].x}, (f32x2){-ap[0].y, ap[0].y}, bb); xfr = n2.x; xfi = n2.y;
;                   *(LAS unsigned*)(xf + r * XB_PITCH + lane * 4) = pk2(n2.x, n2.y); }
;                 { const f32x2 bb = {bf_at(bre0, bre1, rb), bf_at(bim0, bim1, rb)};
;                   const f32x2 n2 = cmac((f32x2){xbr, xbi}, (f32x2){ap[1].x, ap[1].x}, (f32x2){-ap[1].y, ap[1].y}, bb); xbr = n2.x; xbi = n2.y;
;                   *(LAS unsigned*)(xbk + rb * XB_PITCH + lane * 4) = pk2(n2.x, n2.y); }
;             }
;             WAVE_LDS_FENCE();
; #pragma unroll
;             for (int ks = 0; ks < 4; ++ks) {
;                 const bf16x8 Xf = *(const LAS bf16x8*)(xf + fr * XB_PITCH + (8 * fq + 32 * ks) * 2);
;                 const bf16x8 Xb = *(const LAS bf16x8*)(xbk + fr * XB_PITCH + (8 * fq + 32 * ks) * 2);
;                 accY[mf] = __builtin_amdgcn_mfma_f32_16x16x32_bf16(Cf[0][ks], Xf, accY[mf], 0, 0, 0);
;                 accY[mb] = __builtin_amdgcn_mfma_f32_16x16x32_bf16(Cf[1][ks], Xb, accY[mb], 0, 0, 0);
;             }
	v_fma_f32 v237, v152, v242, v237
	v_fma_f32 v233, v36, v242, v233
	v_fma_f32 v237, v37, v238, v237
	v_cvt_pk_bf16_f32 v128, v206, v210
	v_cvt_pk_bf16_f32 v136, v233, v237
	v_add_u32_e32 v193, 0x3080, v103
	v_add_u32_e32 v254, 0x3d40, v103
	v_fma_f32 v207, v150, v206, v207
	v_fma_f32 v211, v150, v210, v211
	v_fma_f32 v207, v16, v210, v207
	v_fma_f32 v211, v17, v206, v211
	v_fma_f32 v232, v152, v233, v232
	v_fma_f32 v236, v152, v237, v236
	v_fma_f32 v232, v36, v237, v232
	v_fma_f32 v236, v37, v233, v236
	v_cvt_pk_bf16_f32 v131, v207, v211
	v_cvt_pk_bf16_f32 v139, v232, v236
	ds_write2_b32 v193, v128, v131 offset0:0 offset1:68
	ds_write2_b32 v254, v139, v136 offset0:136 offset1:204
	v_fma_f32 v208, v150, v207, v208
	v_fma_f32 v212, v150, v211, v212
	v_fma_f32 v208, v16, v211, v208
	v_fma_f32 v212, v17, v207, v212
	v_fma_f32 v231, v152, v232, v231
	v_fma_f32 v235, v152, v236, v235
	v_fma_f32 v231, v36, v236, v231
	v_fma_f32 v235, v37, v232, v235
	v_cvt_pk_bf16_f32 v132, v208, v212
	v_cvt_pk_bf16_f32 v143, v231, v235
	v_fma_f32 v209, v150, v208, v209
	v_fma_f32 v213, v150, v212, v213
	v_fma_f32 v209, v16, v212, v209
	v_fma_f32 v213, v17, v208, v213
	v_fma_f32 v230, v152, v231, v230
	v_fma_f32 v234, v152, v235, v234
	v_fma_f32 v230, v36, v235, v230
	v_fma_f32 v234, v37, v231, v234
	v_cvt_pk_bf16_f32 v135, v209, v213
	v_cvt_pk_bf16_f32 v187, v230, v234
	ds_write2_b32 v193, v132, v135 offset0:136 offset1:204
	ds_write2_b32 v254, v187, v143 offset0:0 offset1:68
	v_fma_f32 v214, v150, v209, v214
	v_fma_f32 v218, v150, v213, v218
	v_fma_f32 v214, v16, v213, v214
	v_fma_f32 v218, v17, v209, v218
	v_fma_f32 v225, v152, v230, v225
	v_fma_f32 v229, v152, v234, v229
	v_fma_f32 v225, v36, v234, v225
	v_fma_f32 v229, v37, v230, v229
	v_cvt_pk_bf16_f32 v128, v214, v218
	v_cvt_pk_bf16_f32 v136, v225, v229
	v_add_u32_e32 v193, 0x34c0, v103
	v_add_u32_e32 v254, 0x3900, v103
	v_fma_f32 v215, v150, v214, v215
	v_fma_f32 v219, v150, v218, v219
	v_fma_f32 v215, v16, v218, v215
	v_fma_f32 v219, v17, v214, v219
	v_fma_f32 v224, v152, v225, v224
	v_fma_f32 v228, v152, v229, v228
	v_fma_f32 v224, v36, v229, v224
	v_fma_f32 v228, v37, v225, v228
	v_cvt_pk_bf16_f32 v131, v215, v219
	v_cvt_pk_bf16_f32 v139, v224, v228
	ds_write2_b32 v193, v128, v131 offset0:0 offset1:68
	ds_write2_b32 v254, v139, v136 offset0:136 offset1:204
	v_fma_f32 v216, v150, v215, v216
	v_fma_f32 v220, v150, v219, v220
	v_fma_f32 v216, v16, v219, v216
	v_fma_f32 v220, v17, v215, v220
	v_fma_f32 v223, v152, v224, v223
	v_fma_f32 v227, v152, v228, v227
	v_fma_f32 v223, v36, v228, v223
	v_fma_f32 v227, v37, v224, v227
	v_cvt_pk_bf16_f32 v132, v216, v220
	v_cvt_pk_bf16_f32 v143, v223, v227
	v_fma_f32 v217, v150, v216, v217
	v_fma_f32 v221, v150, v220, v221
	v_fma_f32 v217, v16, v220, v217
	v_fma_f32 v221, v17, v216, v221
	v_fma_f32 v222, v152, v223, v222
	v_fma_f32 v226, v152, v227, v226
	v_fma_f32 v222, v36, v227, v222
	v_fma_f32 v226, v37, v223, v226
	v_cvt_pk_bf16_f32 v135, v217, v221
	v_cvt_pk_bf16_f32 v187, v222, v226
	ds_write2_b32 v193, v132, v135 offset0:136 offset1:204
	ds_write2_b32 v254, v187, v143 offset0:0 offset1:68
	v_mov_b32_e32 v114, v217
	v_mov_b32_e32 v119, v221
	v_mov_b32_e32 v121, v222
	v_mov_b32_e32 v127, v226
	ds_read_b128 v[188:191], v110 offset:10240
	ds_read_b128 v[194:197], v110 offset:10304
	ds_read_b128 v[198:201], v110 offset:10368
	ds_read_b128 v[202:205], v110 offset:10432
	ds_read_b128 v[206:209], v110 offset:14592
	ds_read_b128 v[210:213], v110 offset:14656
	ds_read_b128 v[214:217], v110 offset:14720
	ds_read_b128 v[218:221], v110 offset:14784
	s_waitcnt lgkmcnt(7)
	v_mfma_f32_16x16x32_bf16 v[52:55], v[0:3], v[188:191], v[52:55]
	s_waitcnt lgkmcnt(3)
	v_mfma_f32_16x16x32_bf16 v[56:59], v[20:23], v[206:209], v[56:59]
	v_mfma_f32_16x16x32_bf16 v[52:55], v[4:7], v[194:197], v[52:55]
	s_waitcnt lgkmcnt(2)
	v_mfma_f32_16x16x32_bf16 v[56:59], v[24:27], v[210:213], v[56:59]
	v_mfma_f32_16x16x32_bf16 v[52:55], v[8:11], v[198:201], v[52:55]
	s_waitcnt lgkmcnt(1)
	v_mfma_f32_16x16x32_bf16 v[56:59], v[28:31], v[214:217], v[56:59]
	v_mfma_f32_16x16x32_bf16 v[52:55], v[12:15], v[202:205], v[52:55]
	s_waitcnt lgkmcnt(0)
	v_mfma_f32_16x16x32_bf16 v[56:59], v[32:35], v[218:221], v[56:59]
	s_setprio 2
	v_mfma_f32_4x4x4_16b_bf16 v[188:191], v[116:117], v[60:61], 0 cbsz:4 abid:0
	v_mfma_f32_4x4x4_16b_bf16 v[194:197], v[116:117], v[68:69], 0 cbsz:4 abid:0
	v_mfma_f32_4x4x4_16b_bf16 v[198:201], v[116:117], v[60:61], 0 cbsz:4 abid:1
	v_mfma_f32_4x4x4_16b_bf16 v[202:205], v[116:117], v[68:69], 0 cbsz:4 abid:1
	v_mfma_f32_4x4x4_16b_bf16 v[206:209], v[116:117], v[60:61], 0 cbsz:4 abid:2
	v_mfma_f32_4x4x4_16b_bf16 v[210:213], v[116:117], v[68:69], 0 cbsz:4 abid:2
	v_mfma_f32_4x4x4_16b_bf16 v[214:217], v[116:117], v[60:61], 0 cbsz:4 abid:3
	v_mfma_f32_4x4x4_16b_bf16 v[218:221], v[116:117], v[68:69], 0 cbsz:4 abid:3
	v_mfma_f32_4x4x4_16b_bf16 v[222:225], v[172:173], v[76:77], 0 cbsz:4 abid:0
	v_mfma_f32_4x4x4_16b_bf16 v[226:229], v[172:173], v[84:85], 0 cbsz:4 abid:0
	v_mfma_f32_4x4x4_16b_bf16 v[230:233], v[172:173], v[76:77], 0 cbsz:4 abid:1
	v_mfma_f32_4x4x4_16b_bf16 v[234:237], v[172:173], v[84:85], 0 cbsz:4 abid:1
	v_mfma_f32_4x4x4_16b_bf16 v[238:241], v[172:173], v[76:77], 0 cbsz:4 abid:2
	v_mfma_f32_4x4x4_16b_bf16 v[242:245], v[172:173], v[84:85], 0 cbsz:4 abid:2
	v_mfma_f32_4x4x4_16b_bf16 v[246:249], v[172:173], v[76:77], 0 cbsz:4 abid:3
	v_mfma_f32_4x4x4_16b_bf16 v[250:253], v[172:173], v[84:85], 0 cbsz:4 abid:3
	v_mfma_f32_4x4x4_16b_bf16 v[188:191], v[116:117], v[62:63], v[188:191] cbsz:4 abid:4
	v_mfma_f32_4x4x4_16b_bf16 v[194:197], v[116:117], v[70:71], v[194:197] cbsz:4 abid:4
; #define LAS __attribute__((address_space(3)))
; __device__ __forceinline__ unsigned pk2(float lo, float hi) { f32x2 v = {lo, hi}; nbf2 r = __builtin_convertvector(v, nbf2); return __builtin_bit_cast(unsigned, r); }
; #define WAVE_LDS_FENCE() asm volatile("s_waitcnt lgkmcnt(0)" ::: "memory")
; __device__ __forceinline__ void s5_out_phase(LAS unsigned char* lds, const bf16_t* UZ, const unsigned char* ws, const float* dskip, bf16_t* YG) {
;     ...
;             for (int nt = 0; nt < 8; ++nt) {
;                 const f32x4 z = {0.f, 0.f, 0.f, 0.f};
;                 const f32x4 cf = __builtin_amdgcn_mfma_f32_16x16x16bf16_1k(Uf[mf], Bf[0][nt], z, 0, 0, 0);
;                 const f32x4 cb = __builtin_amdgcn_mfma_f32_16x16x16bf16_1k(Uf[mb], Bf[1][nt], z, 0, 0, 0);
;                 u32x2 wf, wb; wf.x = pk2(cf[0], cf[1]); wf.y = pk2(cf[2], cf[3]); wb.x = pk2(cb[0], cb[1]); wb.y = pk2(cb[2], cb[3]);
;                 *(LAS u32x2*)(wl + nt * 640 + wofs) = wf;
;                 *(LAS u32x2*)(wl + BUT_BYTES + nt * 640 + wofs) = wb;
;             }
;             WAVE_LDS_FENCE();
;             const LAS unsigned char* rp = wl + lane * 80;
;             const u32x4 fre0 = *(const LAS u32x4*)(rp), fre1 = *(const LAS u32x4*)(rp + 16), fim0 = *(const LAS u32x4*)(rp + 32), fim1 = *(const LAS u32x4*)(rp + 48);
;             const u32x4 bre0 = *(const LAS u32x4*)(rp + BUT_BYTES), bre1 = *(const LAS u32x4*)(rp + BUT_BYTES + 16), bim0 = *(const LAS u32x4*)(rp + BUT_BYTES + 32), bim1 = *(const LAS u32x4*)(rp + BUT_BYTES + 48);
;             LAS unsigned char* xf = wl + 2 * BUT_BYTES; LAS unsigned char* xbk = xf + XB_BYTES;
; #pragma unroll
;             for (int rr = 0; rr < 16; ++rr) {
;                 const int r = rr, rb = 15 - rr;
;                 { const f32x2 bb = {bf_at(fre0, fre1, r), bf_at(fim0, fim1, r)};
;                   const f32x2 n2 = cmac((f32x2){xfr, xfi}, (f32x2){ap[0].x, ap[0].x}, (f32x2){-ap[0].y, ap[0].y}, bb); xfr = n2.x; xfi = n2.y;
;                   *(LAS unsigned*)(xf + r * XB_PITCH + lane * 4) = pk2(n2.x, n2.y); }
;                 { const f32x2 bb = {bf_at(bre0, bre1, rb), bf_at(bim0, bim1, rb)};
;                   const f32x2 n2 = cmac((f32x2){xbr, xbi}, (f32x2){ap[1].x, ap[1].x}, (f32x2){-ap[1].y, ap[1].y}, bb); xbr = n2.x; xbi = n2.y;
;                   *(LAS unsigned*)(xbk + rb * XB_PITCH + lane * 4) = pk2(n2.x, n2.y); }
;             }
	v_mfma_f32_4x4x4_16b_bf16 v[198:201], v[116:117], v[62:63], v[198:201] cbsz:4 abid:5
	v_mfma_f32_4x4x4_16b_bf16 v[202:205], v[116:117], v[70:71], v[202:205] cbsz:4 abid:5
	v_mfma_f32_4x4x4_16b_bf16 v[206:209], v[116:117], v[62:63], v[206:209] cbsz:4 abid:6
	v_mfma_f32_4x4x4_16b_bf16 v[210:213], v[116:117], v[70:71], v[210:213] cbsz:4 abid:6
	v_mfma_f32_4x4x4_16b_bf16 v[214:217], v[116:117], v[62:63], v[214:217] cbsz:4 abid:7
	v_mfma_f32_4x4x4_16b_bf16 v[218:221], v[116:117], v[70:71], v[218:221] cbsz:4 abid:7
	v_mfma_f32_4x4x4_16b_bf16 v[222:225], v[172:173], v[78:79], v[222:225] cbsz:4 abid:4
	v_mfma_f32_4x4x4_16b_bf16 v[226:229], v[172:173], v[86:87], v[226:229] cbsz:4 abid:4
	v_mfma_f32_4x4x4_16b_bf16 v[230:233], v[172:173], v[78:79], v[230:233] cbsz:4 abid:5
	v_mfma_f32_4x4x4_16b_bf16 v[234:237], v[172:173], v[86:87], v[234:237] cbsz:4 abid:5
	v_mfma_f32_4x4x4_16b_bf16 v[238:241], v[172:173], v[78:79], v[238:241] cbsz:4 abid:6
	v_mfma_f32_4x4x4_16b_bf16 v[242:245], v[172:173], v[86:87], v[242:245] cbsz:4 abid:6
	v_mfma_f32_4x4x4_16b_bf16 v[246:249], v[172:173], v[78:79], v[246:249] cbsz:4 abid:7
	v_mfma_f32_4x4x4_16b_bf16 v[250:253], v[172:173], v[86:87], v[250:253] cbsz:4 abid:7
	v_mfma_f32_4x4x4_16b_bf16 v[188:191], v[116:117], v[64:65], v[188:191] cbsz:4 abid:8
	v_mfma_f32_4x4x4_16b_bf16 v[194:197], v[116:117], v[72:73], v[194:197] cbsz:4 abid:8
	v_mfma_f32_4x4x4_16b_bf16 v[198:201], v[116:117], v[64:65], v[198:201] cbsz:4 abid:9
	v_mfma_f32_4x4x4_16b_bf16 v[202:205], v[116:117], v[72:73], v[202:205] cbsz:4 abid:9
	v_mfma_f32_4x4x4_16b_bf16 v[206:209], v[116:117], v[64:65], v[206:209] cbsz:4 abid:10
	v_mfma_f32_4x4x4_16b_bf16 v[210:213], v[116:117], v[72:73], v[210:213] cbsz:4 abid:10
	v_mfma_f32_4x4x4_16b_bf16 v[214:217], v[116:117], v[64:65], v[214:217] cbsz:4 abid:11
	v_mfma_f32_4x4x4_16b_bf16 v[218:221], v[116:117], v[72:73], v[218:221] cbsz:4 abid:11
	v_mfma_f32_4x4x4_16b_bf16 v[222:225], v[172:173], v[80:81], v[222:225] cbsz:4 abid:8
	v_mfma_f32_4x4x4_16b_bf16 v[226:229], v[172:173], v[88:89], v[226:229] cbsz:4 abid:8
	v_mfma_f32_4x4x4_16b_bf16 v[230:233], v[172:173], v[80:81], v[230:233] cbsz:4 abid:9
	v_mfma_f32_4x4x4_16b_bf16 v[234:237], v[172:173], v[88:89], v[234:237] cbsz:4 abid:9
	v_mfma_f32_4x4x4_16b_bf16 v[238:241], v[172:173], v[80:81], v[238:241] cbsz:4 abid:10
	v_mfma_f32_4x4x4_16b_bf16 v[242:245], v[172:173], v[88:89], v[242:245] cbsz:4 abid:10
	v_mfma_f32_4x4x4_16b_bf16 v[246:249], v[172:173], v[80:81], v[246:249] cbsz:4 abid:11
	v_mfma_f32_4x4x4_16b_bf16 v[250:253], v[172:173], v[88:89], v[250:253] cbsz:4 abid:11
	v_mfma_f32_4x4x4_16b_bf16 v[188:191], v[116:117], v[66:67], v[188:191] cbsz:4 abid:12
	v_mfma_f32_4x4x4_16b_bf16 v[194:197], v[116:117], v[74:75], v[194:197] cbsz:4 abid:12
	v_mfma_f32_4x4x4_16b_bf16 v[198:201], v[116:117], v[66:67], v[198:201] cbsz:4 abid:13
	v_mfma_f32_4x4x4_16b_bf16 v[202:205], v[116:117], v[74:75], v[202:205] cbsz:4 abid:13
	v_mfma_f32_4x4x4_16b_bf16 v[206:209], v[116:117], v[66:67], v[206:209] cbsz:4 abid:14
	v_mfma_f32_4x4x4_16b_bf16 v[210:213], v[116:117], v[74:75], v[210:213] cbsz:4 abid:14
	v_mfma_f32_4x4x4_16b_bf16 v[214:217], v[116:117], v[66:67], v[214:217] cbsz:4 abid:15
	v_mfma_f32_4x4x4_16b_bf16 v[218:221], v[116:117], v[74:75], v[218:221] cbsz:4 abid:15
	v_mfma_f32_4x4x4_16b_bf16 v[222:225], v[172:173], v[82:83], v[222:225] cbsz:4 abid:12
	v_mfma_f32_4x4x4_16b_bf16 v[226:229], v[172:173], v[90:91], v[226:229] cbsz:4 abid:12
	v_mfma_f32_4x4x4_16b_bf16 v[230:233], v[172:173], v[82:83], v[230:233] cbsz:4 abid:13
	v_mfma_f32_4x4x4_16b_bf16 v[234:237], v[172:173], v[90:91], v[234:237] cbsz:4 abid:13
	v_mfma_f32_4x4x4_16b_bf16 v[238:241], v[172:173], v[82:83], v[238:241] cbsz:4 abid:14
	v_mfma_f32_4x4x4_16b_bf16 v[242:245], v[172:173], v[90:91], v[242:245] cbsz:4 abid:14
	v_mfma_f32_4x4x4_16b_bf16 v[246:249], v[172:173], v[82:83], v[246:249] cbsz:4 abid:15
	v_mfma_f32_4x4x4_16b_bf16 v[250:253], v[172:173], v[90:91], v[250:253] cbsz:4 abid:15
	s_setprio 0
	v_fma_f32 v188, v150, v114, v188
	v_fma_f32 v194, v150, v119, v194
	v_fma_f32 v188, v16, v119, v188
	v_fma_f32 v194, v17, v114, v194
	v_fma_f32 v249, v152, v121, v249
	v_fma_f32 v253, v152, v127, v253
	v_fma_f32 v249, v36, v127, v249
	v_fma_f32 v253, v37, v121, v253
	v_cvt_pk_bf16_f32 v128, v188, v194
	v_cvt_pk_bf16_f32 v136, v249, v253
	v_add_u32_e32 v193, 0x2800, v103
	v_add_u32_e32 v254, 0x45c0, v103
	v_fma_f32 v189, v150, v188, v189
	v_fma_f32 v195, v150, v194, v195
	v_fma_f32 v189, v16, v194, v189
	v_fma_f32 v195, v17, v188, v195
	v_fma_f32 v248, v152, v249, v248
	v_fma_f32 v252, v152, v253, v252
	v_fma_f32 v248, v36, v253, v248
	v_fma_f32 v252, v37, v249, v252
	v_cvt_pk_bf16_f32 v131, v189, v195
	v_cvt_pk_bf16_f32 v139, v248, v252
	ds_write2_b32 v193, v128, v131 offset0:0 offset1:68
	ds_write2_b32 v254, v139, v136 offset0:136 offset1:204
	v_fma_f32 v190, v150, v189, v190
	v_fma_f32 v196, v150, v195, v196
	v_fma_f32 v190, v16, v195, v190
	v_fma_f32 v196, v17, v189, v196
	v_fma_f32 v247, v152, v248, v247
	v_fma_f32 v251, v152, v252, v251
	v_fma_f32 v247, v36, v252, v247
	v_fma_f32 v251, v37, v248, v251
	v_cvt_pk_bf16_f32 v132, v190, v196
	v_cvt_pk_bf16_f32 v143, v247, v251
	v_fma_f32 v191, v150, v190, v191
	v_fma_f32 v197, v150, v196, v197
	v_fma_f32 v191, v16, v196, v191
	v_fma_f32 v197, v17, v190, v197
	v_fma_f32 v246, v152, v247, v246
	v_fma_f32 v250, v152, v251, v250
	v_fma_f32 v246, v36, v251, v246
	v_fma_f32 v250, v37, v247, v250
	v_cvt_pk_bf16_f32 v135, v191, v197
	v_cvt_pk_bf16_f32 v187, v246, v250
	ds_write2_b32 v193, v132, v135 offset0:136 offset1:204
	ds_write2_b32 v254, v187, v143 offset0:0 offset1:68
; #define LAS __attribute__((address_space(3)))
; __device__ __forceinline__ unsigned pk2(float lo, float hi) { f32x2 v = {lo, hi}; nbf2 r = __builtin_convertvector(v, nbf2); return __builtin_bit_cast(unsigned, r); }
; #define WAVE_LDS_FENCE() asm volatile("s_waitcnt lgkmcnt(0)" ::: "memory")
; __device__ __forceinline__ float bf_at(const u32x4& lo, const u32x4& hi, int r) { const unsigned w = (r < 8 ? lo : hi)[(r & 7) >> 1]; return (r & 1) ? bf_hi(w) : bf_lo(w); }
; __device__ __forceinline__ void s5_out_phase(LAS unsigned char* lds, const bf16_t* UZ, const unsigned char* ws, const float* dskip, bf16_t* YG) {
;     ...
; #pragma unroll
;             for (int rr = 0; rr < 16; ++rr) {
;                 const int r = rr, rb = 15 - rr;
;                 { const f32x2 bb = {bf_at(fre0, fre1, r), bf_at(fim0, fim1, r)};
;                   const f32x2 n2 = cmac((f32x2){xfr, xfi}, (f32x2){ap[0].x, ap[0].x}, (f32x2){-ap[0].y, ap[0].y}, bb); xfr = n2.x; xfi = n2.y;
;                   *(LAS unsigned*)(xf + r * XB_PITCH + lane * 4) = pk2(n2.x, n2.y); }
;                 { const f32x2 bb = {bf_at(bre0, bre1, rb), bf_at(bim0, bim1, rb)};
;                   const f32x2 n2 = cmac((f32x2){xbr, xbi}, (f32x2){ap[1].x, ap[1].x}, (f32x2){-ap[1].y, ap[1].y}, bb); xbr = n2.x; xbi = n2.y;
;                   *(LAS unsigned*)(xbk + rb * XB_PITCH + lane * 4) = pk2(n2.x, n2.y); }
;             }
;             WAVE_LDS_FENCE();
; #pragma unroll
;             for (int ks = 0; ks < 4; ++ks) {
;                 const bf16x8 Xf = *(const LAS bf16x8*)(xf + fr * XB_PITCH + (8 * fq + 32 * ks) * 2);
;                 const bf16x8 Xb = *(const LAS bf16x8*)(xbk + fr * XB_PITCH + (8 * fq + 32 * ks) * 2);
;                 accY[mf] = __builtin_amdgcn_mfma_f32_16x16x32_bf16(Cf[0][ks], Xf, accY[mf], 0, 0, 0);
;                 accY[mb] = __builtin_amdgcn_mfma_f32_16x16x32_bf16(Cf[1][ks], Xb, accY[mb], 0, 0, 0);
;             }
	v_fma_f32 v198, v150, v191, v198
	v_fma_f32 v202, v150, v197, v202
	v_fma_f32 v198, v16, v197, v198
	v_fma_f32 v202, v17, v191, v202
	v_fma_f32 v241, v152, v246, v241
	v_fma_f32 v245, v152, v250, v245
	v_fma_f32 v241, v36, v250, v241
	v_fma_f32 v245, v37, v246, v245
	v_cvt_pk_bf16_f32 v128, v198, v202
	v_cvt_pk_bf16_f32 v136, v241, v245
	v_add_u32_e32 v193, 0x2c40, v103
	v_add_u32_e32 v254, 0x4180, v103
	v_fma_f32 v199, v150, v198, v199
	v_fma_f32 v203, v150, v202, v203
	v_fma_f32 v199, v16, v202, v199
	v_fma_f32 v203, v17, v198, v203
	v_fma_f32 v240, v152, v241, v240
	v_fma_f32 v244, v152, v245, v244
	v_fma_f32 v240, v36, v245, v240
	v_fma_f32 v244, v37, v241, v244
	v_cvt_pk_bf16_f32 v131, v199, v203
	v_cvt_pk_bf16_f32 v139, v240, v244
	ds_write2_b32 v193, v128, v131 offset0:0 offset1:68
	ds_write2_b32 v254, v139, v136 offset0:136 offset1:204
	v_fma_f32 v200, v150, v199, v200
	v_fma_f32 v204, v150, v203, v204
	v_fma_f32 v200, v16, v203, v200
	v_fma_f32 v204, v17, v199, v204
	v_fma_f32 v239, v152, v240, v239
	v_fma_f32 v243, v152, v244, v243
	v_fma_f32 v239, v36, v244, v239
	v_fma_f32 v243, v37, v240, v243
	v_cvt_pk_bf16_f32 v132, v200, v204
	v_cvt_pk_bf16_f32 v143, v239, v243
	v_fma_f32 v201, v150, v200, v201
	v_fma_f32 v205, v150, v204, v205
	v_fma_f32 v201, v16, v204, v201
	v_fma_f32 v205, v17, v200, v205
	v_fma_f32 v238, v152, v239, v238
	v_fma_f32 v242, v152, v243, v242
	v_fma_f32 v238, v36, v243, v238
	v_fma_f32 v242, v37, v239, v242
	v_cvt_pk_bf16_f32 v135, v201, v205
	v_cvt_pk_bf16_f32 v187, v238, v242
	ds_write2_b32 v193, v132, v135 offset0:136 offset1:204
	ds_write2_b32 v254, v187, v143 offset0:0 offset1:68
	v_fma_f32 v206, v150, v201, v206
	v_fma_f32 v210, v150, v205, v210
	v_fma_f32 v206, v16, v205, v206
	v_fma_f32 v210, v17, v201, v210
	v_fma_f32 v233, v152, v238, v233
	v_fma_f32 v237, v152, v242, v237
	v_fma_f32 v233, v36, v242, v233
	v_fma_f32 v237, v37, v238, v237
	v_cvt_pk_bf16_f32 v128, v206, v210
	v_cvt_pk_bf16_f32 v136, v233, v237
	v_add_u32_e32 v193, 0x3080, v103
	v_add_u32_e32 v254, 0x3d40, v103
	v_fma_f32 v207, v150, v206, v207
	v_fma_f32 v211, v150, v210, v211
	v_fma_f32 v207, v16, v210, v207
	v_fma_f32 v211, v17, v206, v211
	v_fma_f32 v232, v152, v233, v232
	v_fma_f32 v236, v152, v237, v236
	v_fma_f32 v232, v36, v237, v232
	v_fma_f32 v236, v37, v233, v236
	v_cvt_pk_bf16_f32 v131, v207, v211
	v_cvt_pk_bf16_f32 v139, v232, v236
	ds_write2_b32 v193, v128, v131 offset0:0 offset1:68
	ds_write2_b32 v254, v139, v136 offset0:136 offset1:204
	v_fma_f32 v208, v150, v207, v208
	v_fma_f32 v212, v150, v211, v212
	v_fma_f32 v208, v16, v211, v208
	v_fma_f32 v212, v17, v207, v212
	v_fma_f32 v231, v152, v232, v231
	v_fma_f32 v235, v152, v236, v235
	v_fma_f32 v231, v36, v236, v231
	v_fma_f32 v235, v37, v232, v235
	v_cvt_pk_bf16_f32 v132, v208, v212
	v_cvt_pk_bf16_f32 v143, v231, v235
	v_fma_f32 v209, v150, v208, v209
	v_fma_f32 v213, v150, v212, v213
	v_fma_f32 v209, v16, v212, v209
	v_fma_f32 v213, v17, v208, v213
	v_fma_f32 v230, v152, v231, v230
	v_fma_f32 v234, v152, v235, v234
	v_fma_f32 v230, v36, v235, v230
	v_fma_f32 v234, v37, v231, v234
	v_cvt_pk_bf16_f32 v135, v209, v213
	v_cvt_pk_bf16_f32 v187, v230, v234
	ds_write2_b32 v193, v132, v135 offset0:136 offset1:204
	ds_write2_b32 v254, v187, v143 offset0:0 offset1:68
	v_fma_f32 v214, v150, v209, v214
	v_fma_f32 v218, v150, v213, v218
	v_fma_f32 v214, v16, v213, v214
	v_fma_f32 v218, v17, v209, v218
	v_fma_f32 v225, v152, v230, v225
	v_fma_f32 v229, v152, v234, v229
	v_fma_f32 v225, v36, v234, v225
	v_fma_f32 v229, v37, v230, v229
	v_cvt_pk_bf16_f32 v128, v214, v218
	v_cvt_pk_bf16_f32 v136, v225, v229
	v_add_u32_e32 v193, 0x34c0, v103
	v_add_u32_e32 v254, 0x3900, v103
	v_fma_f32 v215, v150, v214, v215
	v_fma_f32 v219, v150, v218, v219
	v_fma_f32 v215, v16, v218, v215
	v_fma_f32 v219, v17, v214, v219
	v_fma_f32 v224, v152, v225, v224
	v_fma_f32 v228, v152, v229, v228
	v_fma_f32 v224, v36, v229, v224
	v_fma_f32 v228, v37, v225, v228
	v_cvt_pk_bf16_f32 v131, v215, v219
	v_cvt_pk_bf16_f32 v139, v224, v228
	ds_write2_b32 v193, v128, v131 offset0:0 offset1:68
	ds_write2_b32 v254, v139, v136 offset0:136 offset1:204
	v_fma_f32 v216, v150, v215, v216
	v_fma_f32 v220, v150, v219, v220
	v_fma_f32 v216, v16, v219, v216
	v_fma_f32 v220, v17, v215, v220
	v_fma_f32 v223, v152, v224, v223
	v_fma_f32 v227, v152, v228, v227
	v_fma_f32 v223, v36, v228, v223
	v_fma_f32 v227, v37, v224, v227
	v_cvt_pk_bf16_f32 v132, v216, v220
	v_cvt_pk_bf16_f32 v143, v223, v227
	v_fma_f32 v217, v150, v216, v217
	v_fma_f32 v221, v150, v220, v221
	v_fma_f32 v217, v16, v220, v217
	v_fma_f32 v221, v17, v216, v221
	v_fma_f32 v222, v152, v223, v222
	v_fma_f32 v226, v152, v227, v226
	v_fma_f32 v222, v36, v227, v222
	v_fma_f32 v226, v37, v223, v226
	v_cvt_pk_bf16_f32 v135, v217, v221
	v_cvt_pk_bf16_f32 v187, v222, v226
	ds_write2_b32 v193, v132, v135 offset0:136 offset1:204
	ds_write2_b32 v254, v187, v143 offset0:0 offset1:68
	v_mov_b32_e32 v114, v217
	v_mov_b32_e32 v119, v221
	v_mov_b32_e32 v121, v222
	v_mov_b32_e32 v127, v226
	ds_read_b128 v[188:191], v110 offset:10240
	ds_read_b128 v[194:197], v110 offset:10304
	ds_read_b128 v[198:201], v110 offset:10368
	ds_read_b128 v[202:205], v110 offset:10432
	ds_read_b128 v[206:209], v110 offset:14592
	ds_read_b128 v[210:213], v110 offset:14656
	ds_read_b128 v[214:217], v110 offset:14720
	ds_read_b128 v[218:221], v110 offset:14784
	s_waitcnt lgkmcnt(7)
	v_mfma_f32_16x16x32_bf16 v[44:47], v[0:3], v[188:191], v[44:47]
	s_waitcnt lgkmcnt(3)
	v_mfma_f32_16x16x32_bf16 v[48:51], v[20:23], v[206:209], v[48:51]
	v_mfma_f32_16x16x32_bf16 v[44:47], v[4:7], v[194:197], v[44:47]
	s_waitcnt lgkmcnt(2)
; __device__ __forceinline__ unsigned pk2(float lo, float hi) { f32x2 v = {lo, hi}; nbf2 r = __builtin_convertvector(v, nbf2); return __builtin_bit_cast(unsigned, r); }
; __device__ __forceinline__ float bf_lo(unsigned w) { return __uint_as_float(w << 16); }
; __device__ __forceinline__ float bf_hi(unsigned w) { return __uint_as_float(w & 0xffff0000u); }
; __device__ __forceinline__ float fast_rcp(float x) { return __builtin_amdgcn_rcpf(x); }
; __device__ __forceinline__ float fast_exp2(float x) { return __builtin_amdgcn_exp2f(x); }
; __device__ __forceinline__ float gelu_f(float v) {
;     const float av = fabsf(v), d = av * 0.2316418882f + 1.0f;
;     const float t = fast_rcp(d);
;     float q = t * 0.5307027145f + (-0.7265760135f); q = q * t + 0.7107068705f; q = q * t + (-0.142248368f); q = q * t + 0.127414796f; q = q * t;
;     const float e = fast_exp2((v * v) * (-0.72134752044f));
;     const float m = v * (q * e), r = v - m;
;     return v < 0.f ? m : r;
; }
; __device__ __forceinline__ void s5_out_phase(LAS unsigned char* lds, const bf16_t* UZ, const unsigned char* ws, const float* dskip, bf16_t* YG) {
;     ...
; #pragma unroll
;         for (int m = 0; m < 4; ++m) {
;             const unsigned u0 = (unsigned)(unsigned short)Uf[m][0] | ((unsigned)(unsigned short)Uf[m][1] << 16), u1 = (unsigned)(unsigned short)Uf[m][2] | ((unsigned)(unsigned short)Uf[m][3] << 16);
;             const float y0 = gelu_f(accY[m][0] + dsk[0] * bf_lo(u0)), y1 = gelu_f(accY[m][1] + dsk[1] * bf_hi(u0));
;             const float y2 = gelu_f(accY[m][2] + dsk[2] * bf_lo(u1)), y3 = gelu_f(accY[m][3] + dsk[3] * bf_hi(u1));
;             u32x2 w; w.x = pk2(y0, y1); w.y = pk2(y2, y3);
;             *(u32x2*)(YG + (size_t)(rowbase + 16 * m + fr) * D + 16 * g + 4 * fq) = w;
	v_mfma_f32_16x16x32_bf16 v[48:51], v[24:27], v[210:213], v[48:51]
	v_mfma_f32_16x16x32_bf16 v[44:47], v[8:11], v[198:201], v[44:47]
	s_waitcnt lgkmcnt(1)
	v_mfma_f32_16x16x32_bf16 v[48:51], v[28:31], v[214:217], v[48:51]
	v_mfma_f32_16x16x32_bf16 v[44:47], v[12:15], v[202:205], v[44:47]
	s_waitcnt lgkmcnt(0)
	v_mfma_f32_16x16x32_bf16 v[48:51], v[32:35], v[218:221], v[48:51]
	v_ashrrev_i32_e32 v167, 31, v166
	s_nop 7
	s_nop 4
	v_lshlrev_b32_e32 v188, 16, v172
	v_and_b32_e32 v189, 0xffff0000, v172
	s_waitcnt vmcnt(0)
	v_pk_fma_f32 v[188:189], v[40:41], v[188:189], v[48:49]
	v_lshlrev_b32_e32 v172, 16, v173
	v_fma_f32 v48, |v188|, s21, 1.0
	v_rcp_f32_e32 v190, v48
	v_fma_f32 v48, |v189|, s21, 1.0
	v_rcp_f32_e32 v191, v48
	v_pk_mul_f32 v[194:195], v[188:189], v[188:189]
	v_and_b32_e32 v173, 0xffff0000, v173
	v_mul_f32_e32 v48, 0xbf38aa3b, v194
	v_exp_f32_e32 v194, v48
	v_mov_b64_e32 v[48:49], s[4:5]
	v_pk_fma_f32 v[196:197], v[190:191], s[2:3], v[48:49] op_sel_hi:[1,0,0]
	v_mul_f32_e32 v114, 0xbf38aa3b, v195
	v_pk_fma_f32 v[196:197], v[190:191], v[196:197], s[8:9] op_sel_hi:[1,1,0]
	v_exp_f32_e32 v195, v114
	v_pk_fma_f32 v[196:197], v[190:191], v[196:197], s[20:21] op_sel_hi:[1,1,0]
	v_pk_fma_f32 v[50:51], v[42:43], v[172:173], v[50:51]
	v_pk_fma_f32 v[196:197], v[190:191], v[196:197], s[22:23] op_sel_hi:[1,1,0]
	v_fma_f32 v121, |v50|, s21, 1.0
	v_pk_mul_f32 v[190:191], v[190:191], v[196:197]
	v_rcp_f32_e32 v172, v121
	v_fma_f32 v121, |v51|, s21, 1.0
	v_pk_mul_f32 v[190:191], v[194:195], v[190:191]
	v_rcp_f32_e32 v173, v121
	v_pk_mul_f32 v[194:195], v[188:189], v[190:191]
	v_pk_fma_f32 v[190:191], v[188:189], v[190:191], v[188:189] neg_lo:[1,0,0] neg_hi:[1,0,0]
	v_cmp_gt_f32_e32 vcc, 0, v189
	s_nop 1
	v_cndmask_b32_e32 v114, v191, v195, vcc
	v_cmp_gt_f32_e32 vcc, 0, v188
	v_pk_mul_f32 v[188:189], v[50:51], v[50:51]
	s_nop 0
	v_mul_f32_e32 v121, 0xbf38aa3b, v188
	v_cndmask_b32_e32 v119, v190, v194, vcc
	v_exp_f32_e32 v188, v121
	v_pk_fma_f32 v[190:191], v[172:173], s[2:3], v[48:49] op_sel_hi:[1,0,0]
	v_mul_f32_e32 v121, 0xbf38aa3b, v189
	v_pk_fma_f32 v[190:191], v[172:173], v[190:191], s[8:9] op_sel_hi:[1,1,0]
	v_exp_f32_e32 v189, v121
	v_pk_fma_f32 v[190:191], v[172:173], v[190:191], s[20:21] op_sel_hi:[1,1,0]
	v_cmp_gt_f32_e32 vcc, 0, v51
	v_pk_fma_f32 v[190:191], v[172:173], v[190:191], s[22:23] op_sel_hi:[1,1,0]
	s_nop 0
	v_pk_mul_f32 v[172:173], v[172:173], v[190:191]
	s_nop 0
	v_pk_mul_f32 v[172:173], v[188:189], v[172:173]
	s_nop 0
	v_pk_mul_f32 v[188:189], v[50:51], v[172:173]
	v_pk_fma_f32 v[172:173], v[50:51], v[172:173], v[50:51] neg_lo:[1,0,0] neg_hi:[1,0,0]
	s_nop 0
	v_cndmask_b32_e32 v51, v173, v189, vcc
	v_cmp_gt_f32_e32 vcc, 0, v50
	v_cvt_pk_bf16_f32 v50, v119, v114
	s_nop 0
	v_cndmask_b32_e32 v121, v172, v188, vcc
	v_lshlrev_b64 v[172:173], 11, v[166:167]
	v_cvt_pk_bf16_f32 v51, v121, v51
	v_lshl_add_u64 v[172:173], v[154:155], 0, v[172:173]
	global_store_dwordx2 v[172:173], v[50:51], off
	v_lshlrev_b32_e32 v50, 16, v170
	v_and_b32_e32 v51, 0xffff0000, v170
	v_pk_fma_f32 v[50:51], v[40:41], v[50:51], v[56:57]
	s_nop 0
	v_fma_f32 v56, |v50|, s21, 1.0
	v_fma_f32 v57, |v51|, s21, 1.0
	v_rcp_f32_e32 v56, v56
	v_rcp_f32_e32 v57, v57
	v_pk_mul_f32 v[172:173], v[50:51], v[50:51]
	v_cmp_gt_f32_e32 vcc, 0, v51
	v_mul_f32_e32 v114, 0xbf38aa3b, v172
	v_exp_f32_e32 v172, v114
	v_pk_fma_f32 v[188:189], v[56:57], s[2:3], v[48:49] op_sel_hi:[1,0,0]
	v_mul_f32_e32 v114, 0xbf38aa3b, v173
	v_pk_fma_f32 v[188:189], v[56:57], v[188:189], s[8:9] op_sel_hi:[1,1,0]
	v_exp_f32_e32 v173, v114
	v_pk_fma_f32 v[188:189], v[56:57], v[188:189], s[20:21] op_sel_hi:[1,1,0]
	s_nop 0
	v_pk_fma_f32 v[188:189], v[56:57], v[188:189], s[22:23] op_sel_hi:[1,1,0]
	s_nop 0
	v_pk_mul_f32 v[56:57], v[56:57], v[188:189]
	s_nop 0
	v_pk_mul_f32 v[56:57], v[172:173], v[56:57]
	s_nop 0
	v_pk_mul_f32 v[172:173], v[50:51], v[56:57]
	v_pk_fma_f32 v[56:57], v[50:51], v[56:57], v[50:51] neg_lo:[1,0,0] neg_hi:[1,0,0]
	v_and_b32_e32 v51, 0xffff0000, v171
	v_cndmask_b32_e32 v114, v57, v173, vcc
	v_cmp_gt_f32_e32 vcc, 0, v50
	v_lshlrev_b32_e32 v50, 16, v171
	v_pk_fma_f32 v[50:51], v[42:43], v[50:51], v[58:59]
	v_cndmask_b32_e32 v119, v56, v172, vcc
	v_fma_f32 v56, |v50|, s21, 1.0
	v_fma_f32 v57, |v51|, s21, 1.0
	v_rcp_f32_e32 v56, v56
	v_rcp_f32_e32 v57, v57
	v_pk_mul_f32 v[58:59], v[50:51], v[50:51]
	v_cmp_gt_f32_e32 vcc, 0, v51
	v_mul_f32_e32 v58, 0xbf38aa3b, v58
	v_pk_fma_f32 v[170:171], v[56:57], s[2:3], v[48:49] op_sel_hi:[1,0,0]
	v_mul_f32_e32 v59, 0xbf38aa3b, v59
	v_exp_f32_e32 v58, v58
	v_pk_fma_f32 v[170:171], v[56:57], v[170:171], s[8:9] op_sel_hi:[1,1,0]
	v_exp_f32_e32 v59, v59
	v_pk_fma_f32 v[170:171], v[56:57], v[170:171], s[20:21] op_sel_hi:[1,1,0]
	v_mov_b64_e32 v[172:173], v[174:175]
	v_pk_fma_f32 v[170:171], v[56:57], v[170:171], s[22:23] op_sel_hi:[1,1,0]
	s_nop 0
	v_pk_mul_f32 v[56:57], v[56:57], v[170:171]
	v_mov_b64_e32 v[170:171], v[176:177]
	v_pk_mul_f32 v[56:57], v[58:59], v[56:57]
	s_nop 0
	v_pk_mul_f32 v[58:59], v[50:51], v[56:57]
	v_pk_fma_f32 v[56:57], v[50:51], v[56:57], v[50:51] neg_lo:[1,0,0] neg_hi:[1,0,0]
	s_nop 0
	v_cndmask_b32_e32 v51, v57, v59, vcc
	v_cmp_gt_f32_e32 vcc, 0, v50
	v_cvt_pk_bf16_f32 v50, v119, v114
	s_nop 0
; __device__ __forceinline__ unsigned pk2(float lo, float hi) { f32x2 v = {lo, hi}; nbf2 r = __builtin_convertvector(v, nbf2); return __builtin_bit_cast(unsigned, r); }
; __device__ __forceinline__ float bf_lo(unsigned w) { return __uint_as_float(w << 16); }
; __device__ __forceinline__ float bf_hi(unsigned w) { return __uint_as_float(w & 0xffff0000u); }
; __device__ __forceinline__ float fast_rcp(float x) { return __builtin_amdgcn_rcpf(x); }
; __device__ __forceinline__ float fast_exp2(float x) { return __builtin_amdgcn_exp2f(x); }
; __device__ __forceinline__ float gelu_f(float v) {
;     const float av = fabsf(v), d = av * 0.2316418882f + 1.0f;
;     const float t = fast_rcp(d);
;     float q = t * 0.5307027145f + (-0.7265760135f); q = q * t + 0.7107068705f; q = q * t + (-0.142248368f); q = q * t + 0.127414796f; q = q * t;
;     const float e = fast_exp2((v * v) * (-0.72134752044f));
;     const float m = v * (q * e), r = v - m;
;     return v < 0.f ? m : r;
; }
; __device__ __forceinline__ void s5_out_phase(LAS unsigned char* lds, const bf16_t* UZ, const unsigned char* ws, const float* dskip, bf16_t* YG) {
;     ...
; #pragma unroll
;         for (int m = 0; m < 4; ++m) {
;             const unsigned u0 = (unsigned)(unsigned short)Uf[m][0] | ((unsigned)(unsigned short)Uf[m][1] << 16), u1 = (unsigned)(unsigned short)Uf[m][2] | ((unsigned)(unsigned short)Uf[m][3] << 16);
;             const float y0 = gelu_f(accY[m][0] + dsk[0] * bf_lo(u0)), y1 = gelu_f(accY[m][1] + dsk[1] * bf_hi(u0));
;             const float y2 = gelu_f(accY[m][2] + dsk[2] * bf_lo(u1)), y3 = gelu_f(accY[m][3] + dsk[3] * bf_hi(u1));
;             u32x2 w; w.x = pk2(y0, y1); w.y = pk2(y2, y3);
;             *(u32x2*)(YG + (size_t)(rowbase + 16 * m + fr) * D + 16 * g + 4 * fq) = w;
;         }
;     }
	v_cndmask_b32_e32 v56, v56, v58, vcc
	v_cvt_pk_bf16_f32 v51, v56, v51
	v_add_u32_e32 v56, 16, v166
	v_ashrrev_i32_e32 v57, 31, v56
	v_lshlrev_b64 v[56:57], 11, v[56:57]
	v_lshl_add_u64 v[56:57], v[154:155], 0, v[56:57]
	global_store_dwordx2 v[56:57], v[50:51], off
	v_lshlrev_b32_e32 v50, 16, v168
	v_and_b32_e32 v51, 0xffff0000, v168
	v_pk_fma_f32 v[50:51], v[40:41], v[50:51], v[52:53]
	s_nop 0
	v_fma_f32 v52, |v50|, s21, 1.0
	v_fma_f32 v53, |v51|, s21, 1.0
	v_rcp_f32_e32 v52, v52
	v_rcp_f32_e32 v53, v53
	v_pk_mul_f32 v[56:57], v[50:51], v[50:51]
	v_cmp_gt_f32_e32 vcc, 0, v51
	v_mul_f32_e32 v56, 0xbf38aa3b, v56
	v_pk_fma_f32 v[58:59], v[52:53], s[2:3], v[48:49] op_sel_hi:[1,0,0]
	v_mul_f32_e32 v57, 0xbf38aa3b, v57
	v_exp_f32_e32 v56, v56
	v_pk_fma_f32 v[58:59], v[52:53], v[58:59], s[8:9] op_sel_hi:[1,1,0]
	v_exp_f32_e32 v57, v57
	v_pk_fma_f32 v[58:59], v[52:53], v[58:59], s[20:21] op_sel_hi:[1,1,0]
	s_nop 0
	v_pk_fma_f32 v[58:59], v[52:53], v[58:59], s[22:23] op_sel_hi:[1,1,0]
	s_nop 0
	v_pk_mul_f32 v[52:53], v[52:53], v[58:59]
	s_nop 0
	v_pk_mul_f32 v[52:53], v[56:57], v[52:53]
	s_nop 0
	v_pk_mul_f32 v[56:57], v[50:51], v[52:53]
	v_pk_fma_f32 v[52:53], v[50:51], v[52:53], v[50:51] neg_lo:[1,0,0] neg_hi:[1,0,0]
	v_and_b32_e32 v51, 0xffff0000, v169
	v_cndmask_b32_e32 v58, v53, v57, vcc
	v_cmp_gt_f32_e32 vcc, 0, v50
	v_lshlrev_b32_e32 v50, 16, v169
	v_pk_fma_f32 v[50:51], v[42:43], v[50:51], v[54:55]
	v_cndmask_b32_e32 v59, v52, v56, vcc
	v_fma_f32 v52, |v50|, s21, 1.0
	v_fma_f32 v53, |v51|, s21, 1.0
	v_rcp_f32_e32 v52, v52
	v_rcp_f32_e32 v53, v53
	v_pk_mul_f32 v[54:55], v[50:51], v[50:51]
	v_cmp_gt_f32_e32 vcc, 0, v51
	v_mul_f32_e32 v54, 0xbf38aa3b, v54
	v_pk_fma_f32 v[56:57], v[52:53], s[2:3], v[48:49] op_sel_hi:[1,0,0]
	v_mul_f32_e32 v55, 0xbf38aa3b, v55
	v_exp_f32_e32 v54, v54
	v_pk_fma_f32 v[56:57], v[52:53], v[56:57], s[8:9] op_sel_hi:[1,1,0]
	v_exp_f32_e32 v55, v55
	v_pk_fma_f32 v[56:57], v[52:53], v[56:57], s[20:21] op_sel_hi:[1,1,0]
	v_mov_b64_e32 v[168:169], v[178:179]
	v_pk_fma_f32 v[56:57], v[52:53], v[56:57], s[22:23] op_sel_hi:[1,1,0]
	s_nop 0
	v_pk_mul_f32 v[52:53], v[52:53], v[56:57]
	s_nop 0
	v_pk_mul_f32 v[52:53], v[54:55], v[52:53]
	s_nop 0
	v_pk_mul_f32 v[54:55], v[50:51], v[52:53]
	v_pk_fma_f32 v[52:53], v[50:51], v[52:53], v[50:51] neg_lo:[1,0,0] neg_hi:[1,0,0]
	s_nop 0
	v_cndmask_b32_e32 v51, v53, v55, vcc
	v_cmp_gt_f32_e32 vcc, 0, v50
	v_cvt_pk_bf16_f32 v50, v59, v58
	s_nop 0
	v_cndmask_b32_e32 v52, v52, v54, vcc
	v_cvt_pk_bf16_f32 v51, v52, v51
	v_add_u32_e32 v52, 32, v166
	v_ashrrev_i32_e32 v53, 31, v52
	v_lshlrev_b64 v[52:53], 11, v[52:53]
	v_lshl_add_u64 v[52:53], v[154:155], 0, v[52:53]
	global_store_dwordx2 v[52:53], v[50:51], off
	v_lshlrev_b32_e32 v50, 16, v116
	v_and_b32_e32 v51, 0xffff0000, v116
	v_pk_fma_f32 v[44:45], v[40:41], v[50:51], v[44:45]
	s_nop 0
	v_fma_f32 v50, |v44|, s21, 1.0
	v_fma_f32 v51, |v45|, s21, 1.0
	v_rcp_f32_e32 v50, v50
	v_rcp_f32_e32 v51, v51
	v_pk_mul_f32 v[52:53], v[44:45], v[44:45]
	v_cmp_gt_f32_e32 vcc, 0, v45
	v_mul_f32_e32 v52, 0xbf38aa3b, v52
	v_pk_fma_f32 v[54:55], v[50:51], s[2:3], v[48:49] op_sel_hi:[1,0,0]
	v_mul_f32_e32 v53, 0xbf38aa3b, v53
	v_exp_f32_e32 v52, v52
	v_pk_fma_f32 v[54:55], v[50:51], v[54:55], s[8:9] op_sel_hi:[1,1,0]
	v_exp_f32_e32 v53, v53
	v_pk_fma_f32 v[54:55], v[50:51], v[54:55], s[20:21] op_sel_hi:[1,1,0]
	s_nop 0
	v_pk_fma_f32 v[54:55], v[50:51], v[54:55], s[22:23] op_sel_hi:[1,1,0]
	s_nop 0
	v_pk_mul_f32 v[50:51], v[50:51], v[54:55]
	s_nop 0
	v_pk_mul_f32 v[50:51], v[52:53], v[50:51]
	s_nop 0
	v_pk_mul_f32 v[52:53], v[44:45], v[50:51]
	v_pk_fma_f32 v[50:51], v[44:45], v[50:51], v[44:45] neg_lo:[1,0,0] neg_hi:[1,0,0]
	v_and_b32_e32 v45, 0xffff0000, v117
	v_cndmask_b32_e32 v53, v51, v53, vcc
	v_cmp_gt_f32_e32 vcc, 0, v44
	v_lshlrev_b32_e32 v44, 16, v117
	v_pk_fma_f32 v[44:45], v[42:43], v[44:45], v[46:47]
	v_cndmask_b32_e32 v52, v50, v52, vcc
	v_fma_f32 v46, |v44|, s21, 1.0
	v_fma_f32 v47, |v45|, s21, 1.0
	v_rcp_f32_e32 v46, v46
	v_rcp_f32_e32 v47, v47
	v_pk_mul_f32 v[50:51], v[44:45], v[44:45]
	v_cmp_gt_f32_e32 vcc, 0, v45
	v_mul_f32_e32 v50, 0xbf38aa3b, v50
	v_pk_fma_f32 v[48:49], v[46:47], s[2:3], v[48:49] op_sel_hi:[1,0,0]
	v_mul_f32_e32 v51, 0xbf38aa3b, v51
	v_exp_f32_e32 v50, v50
	v_pk_fma_f32 v[48:49], v[46:47], v[48:49], s[8:9] op_sel_hi:[1,1,0]
	v_exp_f32_e32 v51, v51
	v_pk_fma_f32 v[48:49], v[46:47], v[48:49], s[20:21] op_sel_hi:[1,1,0]
	v_mov_b64_e32 v[116:117], v[180:181]
	v_pk_fma_f32 v[48:49], v[46:47], v[48:49], s[22:23] op_sel_hi:[1,1,0]
	s_nop 0
	v_pk_mul_f32 v[46:47], v[46:47], v[48:49]
	s_nop 0
	v_pk_mul_f32 v[46:47], v[50:51], v[46:47]
	s_nop 0
	v_pk_mul_f32 v[48:49], v[44:45], v[46:47]
	v_pk_fma_f32 v[46:47], v[44:45], v[46:47], v[44:45] neg_lo:[1,0,0] neg_hi:[1,0,0]
	s_nop 0
	v_cndmask_b32_e32 v45, v47, v49, vcc
	v_cmp_gt_f32_e32 vcc, 0, v44
	v_cvt_pk_bf16_f32 v44, v52, v53
	s_nop 0
	v_cndmask_b32_e32 v46, v46, v48, vcc
	v_cvt_pk_bf16_f32 v45, v46, v45
	v_add_u32_e32 v46, 48, v166
	v_ashrrev_i32_e32 v47, 31, v46
	v_lshlrev_b64 v[46:47], 11, v[46:47]
	v_lshl_add_u64 v[46:47], v[154:155], 0, v[46:47]
	v_add_u32_e32 v166, s3, v166
	s_andn2_b64 vcc, exec, s[24:25]
	global_store_dwordx2 v[46:47], v[44:45], off
	s_cbranch_vccz .LBB0_762
